# v39 + input-projection epilogue, rotary tiles: the four table-vector loads of a 16-row group issued together (second pair into spare registers), counted waits instead of full drains
# baseline (speedup 1.0000x reference)
; __device__ __forceinline__ unsigned cvt_pk_bf16(float lo, float hi) { const f32x2_cv v = {lo, hi}; const bf16x2_cv b = __builtin_convertvector(v, bf16x2_cv); return __builtin_bit_cast(unsigned, b); }
;     DI void operator()(const f32x4 (&acc)[2][2][4][2], const Unit& u, int wr, int wc, int fr, int fq) const {
;     ...
;                     int pos, jc, L; row_info(g, row, pos, jc, L);
;                     const f32x4* rp = (const f32x4*)(rot + ((size_t)pos * 32 + 8 * fq) * 2);
;                     const float e1 = exp2f((float)(jc + 1) * lg);
;                     const float sa = pn == 0 ? e1 : 0.125f / e1, sb = (g == 0 && row >= 8720) ? 0.f : 0.125f * exp2f((float)(L - 1 - jc) * lg);
;                     bf16_t* d0 = gb + (size_t)(pn == 0 ? CP_QINR : CP_KINR) * G0ROWS + (size_t)row * 256 + wc * 64 + 8 * fq;
;                     bf16_t* d1 = gb + (size_t)CP_KSTR * G0ROWS + (size_t)row * 256 + wc * 64 + 8 * fq;
; #pragma unroll
;                     for (int n = 0; n < 2; ++n) {
;                         const f32x4 cs0 = rp[2 * n], cs1 = rp[2 * n + 1];
;                         const f32x4 x1 = acc[ai][0][m][n], x2 = acc[ai][1][m][n];
;                         f32x4 o1, o2;
;                         o1[0] = x1[0] * cs0[0] - x2[0] * cs0[1]; o2[0] = x1[0] * cs0[1] + x2[0] * cs0[0];
;                         o1[1] = x1[1] * cs0[2] - x2[1] * cs0[3]; o2[1] = x1[1] * cs0[3] + x2[1] * cs0[2];
;                         o1[2] = x1[2] * cs1[0] - x2[2] * cs1[1]; o2[2] = x1[2] * cs1[1] + x2[2] * cs1[0];
;                         o1[3] = x1[3] * cs1[2] - x2[3] * cs1[3]; o2[3] = x1[3] * cs1[3] + x2[3] * cs1[2];
;                         u32x2 w; w.x = cvt_pk_bf16(o1[0] * sa, o1[1] * sa); w.y = cvt_pk_bf16(o1[2] * sa, o1[3] * sa); *(u32x2*)(d0 + 4 * n) = w;
;                         w.x = cvt_pk_bf16(o2[0] * sa, o2[1] * sa); w.y = cvt_pk_bf16(o2[2] * sa, o2[3] * sa); *(u32x2*)(d0 + 32 + 4 * n) = w;
;                         if (pn == 1) {
;                             w.x = cvt_pk_bf16(o1[0] * sb, o1[1] * sb); w.y = cvt_pk_bf16(o1[2] * sb, o1[3] * sb); *(u32x2*)(d1 + 4 * n) = w;
;                             w.x = cvt_pk_bf16(o2[0] * sb, o2[1] * sb); w.y = cvt_pk_bf16(o2[2] * sb, o2[3] * sb); *(u32x2*)(d1 + 32 + 4 * n) = w;
;                         }
.LBB0_300:
	s_andn2_saveexec_b64 s[4:5], s[4:5]
	v_and_b32_e32 v32, 0x7ff, v148
	v_add_u32_e32 v32, 16, v32
	v_and_b32_e32 v149, 63, v148
	v_mov_b32_e32 v150, 64
	s_or_b64 exec, exec, s[4:5]
	v_lshlrev_b64 v[152:153], 8, v[32:33]
	v_lshl_add_u64 v[152:153], v[140:141], 0, v[152:153]
	global_load_dwordx4 v[164:167], v[152:153], off
	global_load_dwordx4 v[168:171], v[152:153], off offset:16
	global_load_dwordx4 v[176:179], v[152:153], off offset:48
	global_load_dwordx4 v[180:183], v[152:153], off offset:32
	v_add_u32_e32 v151, 1, v149
	v_xad_u32 v150, v149, -1, v150
	v_cvt_f32_u32_e32 v151, v151
	v_cvt_f32_i32_e32 v150, v150
	s_cmp_eq_u32 s40, 0
	s_cselect_b64 s[42:43], -1, 0
	v_mul_f32_e32 v154, v161, v151
	v_mul_f32_e32 v155, v161, v150
	v_cmp_gt_f32_e32 vcc, s22, v154
	v_cmp_gt_f32_e64 s[6:7], s22, v155
	s_and_b64 s[0:1], s[42:43], exec
	v_cndmask_b32_e32 v154, 0, v232, vcc
	v_cndmask_b32_e64 v155, 0, v232, s[6:7]
	v_fmac_f32_e32 v154, v161, v151
	v_fmac_f32_e32 v155, v161, v150
	v_exp_f32_e32 v150, v154
	v_exp_f32_e32 v151, v155
	v_cndmask_b32_e32 v154, 0, v234, vcc
	v_cndmask_b32_e64 v155, 0, v234, s[6:7]
	v_ldexp_f32 v150, v150, v154
	v_div_scale_f32 v154, s[0:1], v150, v150, s80
	v_ldexp_f32 v151, v151, v155
	v_rcp_f32_e32 v155, v154
	v_div_scale_f32 v158, vcc, s80, v150, s80
	v_cmp_lt_i32_e64 s[4:5], s24, v148
	v_fma_f32 v159, -v154, v155, 1.0
	v_fmac_f32_e32 v155, v159, v155
	v_mul_f32_e32 v159, v158, v155
	v_fma_f32 v172, -v154, v159, v158
	v_fmac_f32_e32 v159, v172, v155
	s_cselect_b32 s2, 0, 0x460000
	s_cmp_eq_u32 s40, 1
	v_fma_f32 v154, -v154, v159, v158
	s_cselect_b64 s[6:7], -1, 0
	s_and_b64 s[0:1], s[44:45], s[4:5]
	v_ashrrev_i32_e32 v149, 31, v148
	v_div_fmas_f32 v154, v154, v155, v159
	s_add_u32 s4, s95, s2
	v_lshlrev_b64 v[156:157], 9, v[148:149]
	v_div_fixup_f32 v154, v154, v150, s80
	s_addc_u32 s5, s97, 0
	v_lshl_add_u64 v[148:149], v[142:143], 0, v[156:157]
	v_cndmask_b32_e64 v154, v154, v150, s[42:43]
	s_lshl_b32 s12, s65, 1
	v_lshl_add_u64 v[156:157], s[4:5], 0, v[156:157]
	v_lshlrev_b32_e32 v32, 1, v138
	v_mul_f32_e32 v151, 0x3e000000, v151
	v_lshl_add_u64 v[156:157], v[156:157], 0, s[12:13]
	v_cndmask_b32_e64 v150, v151, 0, s[0:1]
	s_cmp_lg_u32 s40, 1
	v_lshl_add_u64 v[156:157], v[156:157], 0, v[32:33]
	s_waitcnt vmcnt(2)
	v_mov_b32_e32 v158, v164
	v_mov_b32_e32 v159, v166
	v_mov_b32_e32 v166, v165
	v_mov_b32_e32 v165, v170
	v_mov_b32_e32 v170, v169
	v_mov_b32_e32 v164, v168
	v_pk_mul_f32 v[168:169], v[122:123], v[166:167]
	v_pk_mul_f32 v[122:123], v[122:123], v[158:159]
	v_pk_mul_f32 v[172:173], v[124:125], v[170:171]
	v_pk_mul_f32 v[124:125], v[124:125], v[164:165]
	v_pk_fma_f32 v[158:159], v[126:127], v[158:159], v[168:169] neg_lo:[0,0,1] neg_hi:[0,0,1]
	v_pk_fma_f32 v[122:123], v[126:127], v[166:167], v[122:123]
	v_pk_fma_f32 v[126:127], v[128:129], v[164:165], v[172:173] neg_lo:[0,0,1] neg_hi:[0,0,1]
	v_pk_fma_f32 v[124:125], v[128:129], v[170:171], v[124:125]
	v_pk_mul_f32 v[128:129], v[158:159], v[154:155] op_sel_hi:[1,0]
	v_pk_mul_f32 v[164:165], v[154:155], v[126:127] op_sel_hi:[0,1]
	v_pk_mul_f32 v[166:167], v[122:123], v[154:155] op_sel_hi:[1,0]
	v_pk_mul_f32 v[168:169], v[154:155], v[124:125] op_sel_hi:[0,1]
	v_cvt_pk_bf16_f32 v128, v128, v129
	v_cvt_pk_bf16_f32 v129, v164, v165
	v_cvt_pk_bf16_f32 v164, v166, v167
	v_cvt_pk_bf16_f32 v165, v168, v169
	global_store_dwordx2 v[156:157], v[128:129], off
	global_store_dwordx2 v[156:157], v[164:165], off offset:64
	s_cbranch_scc1 .LBB0_304
	v_pk_mul_f32 v[128:129], v[158:159], v[150:151] op_sel_hi:[1,0]
	v_pk_mul_f32 v[126:127], v[126:127], v[150:151] op_sel_hi:[1,0]
	v_pk_mul_f32 v[122:123], v[122:123], v[150:151] op_sel_hi:[1,0]
	v_pk_mul_f32 v[124:125], v[124:125], v[150:151] op_sel_hi:[1,0]
	v_cvt_pk_bf16_f32 v128, v128, v129
	v_cvt_pk_bf16_f32 v129, v126, v127
	v_cvt_pk_bf16_f32 v122, v122, v123
	v_cvt_pk_bf16_f32 v123, v124, v125
	global_store_dwordx2 v[148:149], v[128:129], off
	global_store_dwordx2 v[148:149], v[122:123], off offset:64
.LBB0_304:
	v_mov_b32_e32 v155, v154
	s_andn2_b64 vcc, exec, s[6:7]
	s_waitcnt vmcnt(2)
	v_mov_b32_e32 v129, v182
	v_mov_b32_e32 v182, v181
	v_mov_b32_e32 v128, v180
	v_pk_mul_f32 v[122:123], v[114:115], v[182:183]
	v_pk_mul_f32 v[114:115], v[114:115], v[128:129]
	v_pk_fma_f32 v[122:123], v[118:119], v[128:129], v[122:123] neg_lo:[0,0,1] neg_hi:[0,0,1]
	v_mov_b32_e32 v129, v178
	v_mov_b32_e32 v178, v177
	v_pk_fma_f32 v[114:115], v[118:119], v[182:183], v[114:115]
	v_mov_b32_e32 v128, v176
	v_pk_mul_f32 v[118:119], v[116:117], v[178:179]
	v_pk_mul_f32 v[116:117], v[116:117], v[128:129]
	v_pk_fma_f32 v[118:119], v[120:121], v[128:129], v[118:119] neg_lo:[0,0,1] neg_hi:[0,0,1]
	v_pk_fma_f32 v[116:117], v[120:121], v[178:179], v[116:117]
	v_pk_mul_f32 v[120:121], v[154:155], v[122:123]
	v_pk_mul_f32 v[176:177], v[154:155], v[118:119]
	v_cvt_pk_bf16_f32 v120, v120, v121
	v_cvt_pk_bf16_f32 v121, v176, v177
	global_store_dwordx2 v[156:157], v[120:121], off offset:8
	v_pk_mul_f32 v[120:121], v[154:155], v[114:115]
	v_pk_mul_f32 v[176:177], v[154:155], v[116:117]
	v_cvt_pk_bf16_f32 v120, v120, v121
	v_cvt_pk_bf16_f32 v121, v176, v177
	global_store_dwordx2 v[156:157], v[120:121], off offset:72
	v_cndmask_b32_e64 v120, 0, 1, s[6:7]
	v_cmp_ne_u32_e64 s[40:41], 1, v120
	s_cbranch_vccnz .LBB0_306
	v_pk_mul_f32 v[120:121], v[150:151], v[122:123] op_sel_hi:[0,1]
	v_pk_mul_f32 v[118:119], v[150:151], v[118:119] op_sel_hi:[0,1]
	v_pk_mul_f32 v[114:115], v[150:151], v[114:115] op_sel_hi:[0,1]
	v_pk_mul_f32 v[116:117], v[150:151], v[116:117] op_sel_hi:[0,1]
	v_cvt_pk_bf16_f32 v120, v120, v121
	v_cvt_pk_bf16_f32 v121, v118, v119
	v_cvt_pk_bf16_f32 v114, v114, v115
	v_cvt_pk_bf16_f32 v115, v116, v117
	global_store_dwordx2 v[148:149], v[120:121], off offset:8
	global_store_dwordx2 v[148:149], v[114:115], off offset:72

; __device__ __forceinline__ unsigned cvt_pk_bf16(float lo, float hi) { const f32x2_cv v = {lo, hi}; const bf16x2_cv b = __builtin_convertvector(v, bf16x2_cv); return __builtin_bit_cast(unsigned, b); }
;     DI void operator()(const f32x4 (&acc)[2][2][4][2], const Unit& u, int wr, int wc, int fr, int fq) const {
;     ...
;                     int pos, jc, L; row_info(g, row, pos, jc, L);
;                     const f32x4* rp = (const f32x4*)(rot + ((size_t)pos * 32 + 8 * fq) * 2);
;                     const float e1 = exp2f((float)(jc + 1) * lg);
;                     const float sa = pn == 0 ? e1 : 0.125f / e1, sb = (g == 0 && row >= 8720) ? 0.f : 0.125f * exp2f((float)(L - 1 - jc) * lg);
;                     bf16_t* d0 = gb + (size_t)(pn == 0 ? CP_QINR : CP_KINR) * G0ROWS + (size_t)row * 256 + wc * 64 + 8 * fq;
;                     bf16_t* d1 = gb + (size_t)CP_KSTR * G0ROWS + (size_t)row * 256 + wc * 64 + 8 * fq;
; #pragma unroll
;                     for (int n = 0; n < 2; ++n) {
;                         const f32x4 cs0 = rp[2 * n], cs1 = rp[2 * n + 1];
;                         const f32x4 x1 = acc[ai][0][m][n], x2 = acc[ai][1][m][n];
;                         f32x4 o1, o2;
;                         o1[0] = x1[0] * cs0[0] - x2[0] * cs0[1]; o2[0] = x1[0] * cs0[1] + x2[0] * cs0[0];
;                         o1[1] = x1[1] * cs0[2] - x2[1] * cs0[3]; o2[1] = x1[1] * cs0[3] + x2[1] * cs0[2];
;                         o1[2] = x1[2] * cs1[0] - x2[2] * cs1[1]; o2[2] = x1[2] * cs1[1] + x2[2] * cs1[0];
;                         o1[3] = x1[3] * cs1[2] - x2[3] * cs1[3]; o2[3] = x1[3] * cs1[3] + x2[3] * cs1[2];
;                         u32x2 w; w.x = cvt_pk_bf16(o1[0] * sa, o1[1] * sa); w.y = cvt_pk_bf16(o1[2] * sa, o1[3] * sa); *(u32x2*)(d0 + 4 * n) = w;
;                         w.x = cvt_pk_bf16(o2[0] * sa, o2[1] * sa); w.y = cvt_pk_bf16(o2[2] * sa, o2[3] * sa); *(u32x2*)(d0 + 32 + 4 * n) = w;
;                         if (pn == 1) {
;                             w.x = cvt_pk_bf16(o1[0] * sb, o1[1] * sb); w.y = cvt_pk_bf16(o1[2] * sb, o1[3] * sb); *(u32x2*)(d1 + 4 * n) = w;
;                             w.x = cvt_pk_bf16(o2[0] * sb, o2[1] * sb); w.y = cvt_pk_bf16(o2[2] * sb, o2[3] * sb); *(u32x2*)(d1 + 32 + 4 * n) = w;
;                         }
.LBB0_312:
	s_andn2_saveexec_b64 s[6:7], s[6:7]
	v_and_b32_e32 v114, 0x7ff, v116
	v_add_u32_e32 v114, 16, v114
	v_and_b32_e32 v117, 63, v116
	v_mov_b32_e32 v121, 64
	s_or_b64 exec, exec, s[6:7]
	v_mov_b32_e32 v115, v33
	v_lshlrev_b64 v[114:115], 8, v[114:115]
	v_lshl_add_u64 v[118:119], v[140:141], 0, v[114:115]
	global_load_dwordx4 v[126:129], v[118:119], off offset:16
	global_load_dwordx4 v[148:151], v[118:119], off
	global_load_dwordx4 v[176:179], v[118:119], off offset:48
	global_load_dwordx4 v[180:183], v[118:119], off offset:32
	v_add_u32_e32 v114, 1, v117
	v_cvt_f32_u32_e32 v114, v114
	v_mul_f32_e32 v115, v161, v114
	v_cmp_gt_f32_e32 vcc, s22, v115
	s_waitcnt vmcnt(2)
	v_mov_b32_e32 v152, v148
	v_cndmask_b32_e32 v115, 0, v232, vcc
	v_fmac_f32_e32 v115, v161, v114
	v_exp_f32_e32 v114, v115
	v_cndmask_b32_e32 v115, 0, v234, vcc
	v_mov_b32_e32 v153, v150
	v_mov_b32_e32 v150, v149
	v_ldexp_f32 v114, v114, v115
	v_div_scale_f32 v115, s[0:1], v114, v114, s80
	v_rcp_f32_e32 v120, v115
	v_mov_b32_e32 v149, v128
	v_mov_b32_e32 v128, v127
	v_mov_b32_e32 v148, v126
	v_fma_f32 v122, -v115, v120, 1.0
	v_fmac_f32_e32 v120, v122, v120
	v_div_scale_f32 v122, vcc, s80, v114, s80
	v_mul_f32_e32 v123, v122, v120
	v_fma_f32 v124, -v115, v123, v122
	v_fmac_f32_e32 v123, v124, v120
	v_fma_f32 v115, -v115, v123, v122
	v_div_fmas_f32 v115, v115, v120, v123
	v_div_fixup_f32 v115, v115, v114, s80
	v_cndmask_b32_e64 v120, v115, v114, s[42:43]
	v_xad_u32 v114, v117, -1, v121
	v_cvt_f32_i32_e32 v114, v114
	v_cmp_lt_i32_e32 vcc, s24, v116
	s_and_b64 s[0:1], s[44:45], vcc
	v_ashrrev_i32_e32 v117, 31, v116
	v_mul_f32_e32 v115, v161, v114
	v_cmp_gt_f32_e32 vcc, s22, v115
	v_pk_mul_f32 v[124:125], v[106:107], v[150:151]
	v_pk_mul_f32 v[106:107], v[106:107], v[152:153]
	v_cndmask_b32_e32 v115, 0, v232, vcc
	v_fmac_f32_e32 v115, v161, v114
	v_exp_f32_e32 v114, v115
	v_lshlrev_b64 v[116:117], 9, v[116:117]
	v_pk_fma_f32 v[124:125], v[110:111], v[152:153], v[124:125] neg_lo:[0,0,1] neg_hi:[0,0,1]
	v_pk_fma_f32 v[106:107], v[110:111], v[150:151], v[106:107]
	v_pk_mul_f32 v[110:111], v[108:109], v[128:129]
	v_lshl_add_u64 v[122:123], s[4:5], 0, v[116:117]
	v_pk_fma_f32 v[110:111], v[112:113], v[148:149], v[110:111] neg_lo:[0,0,1] neg_hi:[0,0,1]
	v_pk_mul_f32 v[108:109], v[108:109], v[148:149]
	v_cndmask_b32_e32 v115, 0, v234, vcc
	v_lshl_add_u64 v[122:123], v[122:123], 0, s[12:13]
	v_pk_fma_f32 v[108:109], v[112:113], v[128:129], v[108:109]
	v_pk_mul_f32 v[112:113], v[124:125], v[120:121] op_sel_hi:[1,0]
	v_pk_mul_f32 v[126:127], v[120:121], v[110:111] op_sel_hi:[0,1]
	v_ldexp_f32 v114, v114, v115
	v_lshl_add_u64 v[122:123], v[122:123], 0, v[32:33]
	v_cvt_pk_bf16_f32 v112, v112, v113
	v_cvt_pk_bf16_f32 v113, v126, v127
	v_mul_f32_e32 v114, 0x3e000000, v114
	global_store_dwordx2 v[122:123], v[112:113], off
	v_pk_mul_f32 v[112:113], v[106:107], v[120:121] op_sel_hi:[1,0]
	v_pk_mul_f32 v[126:127], v[120:121], v[108:109] op_sel_hi:[0,1]
	v_cndmask_b32_e64 v114, v114, 0, s[0:1]
	v_lshl_add_u64 v[116:117], v[142:143], 0, v[116:117]
	v_cvt_pk_bf16_f32 v112, v112, v113
	v_cvt_pk_bf16_f32 v113, v126, v127
	s_and_b64 vcc, exec, s[40:41]
	global_store_dwordx2 v[122:123], v[112:113], off offset:64
	s_cbranch_vccnz .LBB0_316
	v_pk_mul_f32 v[112:113], v[124:125], v[114:115] op_sel_hi:[1,0]
	v_pk_mul_f32 v[110:111], v[110:111], v[114:115] op_sel_hi:[1,0]
	v_pk_mul_f32 v[106:107], v[106:107], v[114:115] op_sel_hi:[1,0]
	v_pk_mul_f32 v[108:109], v[108:109], v[114:115] op_sel_hi:[1,0]
	v_cvt_pk_bf16_f32 v112, v112, v113
	v_cvt_pk_bf16_f32 v113, v110, v111
	v_cvt_pk_bf16_f32 v106, v106, v107
	v_cvt_pk_bf16_f32 v107, v108, v109
	global_store_dwordx2 v[116:117], v[112:113], off
	global_store_dwordx2 v[116:117], v[106:107], off offset:64
.LBB0_316:
	v_mov_b32_e32 v121, v120
	s_and_b64 vcc, exec, s[40:41]
	s_waitcnt vmcnt(2)
	v_mov_b32_e32 v113, v182
	v_mov_b32_e32 v182, v181
	v_mov_b32_e32 v112, v180
	v_pk_mul_f32 v[106:107], v[98:99], v[182:183]
	v_pk_mul_f32 v[98:99], v[98:99], v[112:113]
	v_pk_fma_f32 v[106:107], v[102:103], v[112:113], v[106:107] neg_lo:[0,0,1] neg_hi:[0,0,1]
	v_mov_b32_e32 v113, v178
	v_mov_b32_e32 v178, v177
	v_pk_fma_f32 v[98:99], v[102:103], v[182:183], v[98:99]
	v_mov_b32_e32 v112, v176
	v_pk_mul_f32 v[102:103], v[100:101], v[178:179]
	v_pk_mul_f32 v[100:101], v[100:101], v[112:113]
	v_pk_fma_f32 v[102:103], v[104:105], v[112:113], v[102:103] neg_lo:[0,0,1] neg_hi:[0,0,1]
	v_pk_fma_f32 v[100:101], v[104:105], v[178:179], v[100:101]
	v_pk_mul_f32 v[104:105], v[120:121], v[106:107]
	v_pk_mul_f32 v[176:177], v[120:121], v[102:103]
	v_cvt_pk_bf16_f32 v104, v104, v105
	v_cvt_pk_bf16_f32 v105, v176, v177
	global_store_dwordx2 v[122:123], v[104:105], off offset:8
	v_pk_mul_f32 v[104:105], v[120:121], v[98:99]
	v_pk_mul_f32 v[176:177], v[120:121], v[100:101]
	v_cvt_pk_bf16_f32 v104, v104, v105
	v_cvt_pk_bf16_f32 v105, v176, v177
	global_store_dwordx2 v[122:123], v[104:105], off offset:72
	s_cbranch_vccnz .LBB0_318
	v_pk_mul_f32 v[104:105], v[114:115], v[106:107] op_sel_hi:[0,1]
	v_pk_mul_f32 v[102:103], v[114:115], v[102:103] op_sel_hi:[0,1]
	v_pk_mul_f32 v[98:99], v[114:115], v[98:99] op_sel_hi:[0,1]
	v_pk_mul_f32 v[100:101], v[114:115], v[100:101] op_sel_hi:[0,1]
	v_cvt_pk_bf16_f32 v104, v104, v105
	v_cvt_pk_bf16_f32 v105, v102, v103
	v_cvt_pk_bf16_f32 v98, v98, v99
	v_cvt_pk_bf16_f32 v99, v100, v101
	global_store_dwordx2 v[116:117], v[104:105], off offset:8
	global_store_dwordx2 v[116:117], v[98:99], off offset:72

; __device__ __forceinline__ unsigned cvt_pk_bf16(float lo, float hi) { const f32x2_cv v = {lo, hi}; const bf16x2_cv b = __builtin_convertvector(v, bf16x2_cv); return __builtin_bit_cast(unsigned, b); }
;     DI void operator()(const f32x4 (&acc)[2][2][4][2], const Unit& u, int wr, int wc, int fr, int fq) const {
;     ...
;                     int pos, jc, L; row_info(g, row, pos, jc, L);
;                     const f32x4* rp = (const f32x4*)(rot + ((size_t)pos * 32 + 8 * fq) * 2);
;                     const float e1 = exp2f((float)(jc + 1) * lg);
;                     const float sa = pn == 0 ? e1 : 0.125f / e1, sb = (g == 0 && row >= 8720) ? 0.f : 0.125f * exp2f((float)(L - 1 - jc) * lg);
;                     bf16_t* d0 = gb + (size_t)(pn == 0 ? CP_QINR : CP_KINR) * G0ROWS + (size_t)row * 256 + wc * 64 + 8 * fq;
;                     bf16_t* d1 = gb + (size_t)CP_KSTR * G0ROWS + (size_t)row * 256 + wc * 64 + 8 * fq;
; #pragma unroll
;                     for (int n = 0; n < 2; ++n) {
;                         const f32x4 cs0 = rp[2 * n], cs1 = rp[2 * n + 1];
;                         const f32x4 x1 = acc[ai][0][m][n], x2 = acc[ai][1][m][n];
;                         f32x4 o1, o2;
;                         o1[0] = x1[0] * cs0[0] - x2[0] * cs0[1]; o2[0] = x1[0] * cs0[1] + x2[0] * cs0[0];
;                         o1[1] = x1[1] * cs0[2] - x2[1] * cs0[3]; o2[1] = x1[1] * cs0[3] + x2[1] * cs0[2];
;                         o1[2] = x1[2] * cs1[0] - x2[2] * cs1[1]; o2[2] = x1[2] * cs1[1] + x2[2] * cs1[0];
;                         o1[3] = x1[3] * cs1[2] - x2[3] * cs1[3]; o2[3] = x1[3] * cs1[3] + x2[3] * cs1[2];
;                         u32x2 w; w.x = cvt_pk_bf16(o1[0] * sa, o1[1] * sa); w.y = cvt_pk_bf16(o1[2] * sa, o1[3] * sa); *(u32x2*)(d0 + 4 * n) = w;
;                         w.x = cvt_pk_bf16(o2[0] * sa, o2[1] * sa); w.y = cvt_pk_bf16(o2[2] * sa, o2[3] * sa); *(u32x2*)(d0 + 32 + 4 * n) = w;
;                         if (pn == 1) {
;                             w.x = cvt_pk_bf16(o1[0] * sb, o1[1] * sb); w.y = cvt_pk_bf16(o1[2] * sb, o1[3] * sb); *(u32x2*)(d1 + 4 * n) = w;
;                             w.x = cvt_pk_bf16(o2[0] * sb, o2[1] * sb); w.y = cvt_pk_bf16(o2[2] * sb, o2[3] * sb); *(u32x2*)(d1 + 32 + 4 * n) = w;
;                         }
.LBB0_324:
	s_andn2_saveexec_b64 s[6:7], s[6:7]
	v_and_b32_e32 v98, 0x7ff, v100
	v_add_u32_e32 v98, 16, v98
	v_and_b32_e32 v101, 63, v100
	v_mov_b32_e32 v105, 64
	s_or_b64 exec, exec, s[6:7]
	v_mov_b32_e32 v99, v33
	v_lshlrev_b64 v[98:99], 8, v[98:99]
	v_lshl_add_u64 v[102:103], v[140:141], 0, v[98:99]
	global_load_dwordx4 v[110:113], v[102:103], off offset:16
	global_load_dwordx4 v[114:117], v[102:103], off
	global_load_dwordx4 v[176:179], v[102:103], off offset:48
	global_load_dwordx4 v[180:183], v[102:103], off offset:32
	v_add_u32_e32 v98, 1, v101
	v_cvt_f32_u32_e32 v98, v98
	v_mul_f32_e32 v99, v161, v98
	v_cmp_gt_f32_e32 vcc, s22, v99
	s_waitcnt vmcnt(2)
	v_mov_b32_e32 v118, v114
	v_cndmask_b32_e32 v99, 0, v232, vcc
	v_fmac_f32_e32 v99, v161, v98
	v_exp_f32_e32 v98, v99
	v_cndmask_b32_e32 v99, 0, v234, vcc
	v_mov_b32_e32 v119, v116
	v_mov_b32_e32 v116, v115
	v_ldexp_f32 v98, v98, v99
	v_div_scale_f32 v99, s[0:1], v98, v98, s80
	v_rcp_f32_e32 v104, v99
	v_mov_b32_e32 v115, v112
	v_mov_b32_e32 v112, v111
	v_mov_b32_e32 v114, v110
	v_fma_f32 v106, -v99, v104, 1.0
	v_fmac_f32_e32 v104, v106, v104
	v_div_scale_f32 v106, vcc, s80, v98, s80
	v_mul_f32_e32 v107, v106, v104
	v_fma_f32 v108, -v99, v107, v106
	v_fmac_f32_e32 v107, v108, v104
	v_fma_f32 v99, -v99, v107, v106
	v_div_fmas_f32 v99, v99, v104, v107
	v_div_fixup_f32 v99, v99, v98, s80
	v_cndmask_b32_e64 v104, v99, v98, s[42:43]
	v_xad_u32 v98, v101, -1, v105
	v_cvt_f32_i32_e32 v98, v98
	v_cmp_lt_i32_e32 vcc, s24, v100
	s_and_b64 s[0:1], s[44:45], vcc
	v_ashrrev_i32_e32 v101, 31, v100
	v_mul_f32_e32 v99, v161, v98
	v_cmp_gt_f32_e32 vcc, s22, v99
	v_pk_mul_f32 v[108:109], v[90:91], v[116:117]
	v_pk_mul_f32 v[90:91], v[90:91], v[118:119]
	v_cndmask_b32_e32 v99, 0, v232, vcc
	v_fmac_f32_e32 v99, v161, v98
	v_exp_f32_e32 v98, v99
	v_lshlrev_b64 v[100:101], 9, v[100:101]
	v_pk_fma_f32 v[108:109], v[94:95], v[118:119], v[108:109] neg_lo:[0,0,1] neg_hi:[0,0,1]
	v_pk_fma_f32 v[90:91], v[94:95], v[116:117], v[90:91]
	v_pk_mul_f32 v[94:95], v[92:93], v[112:113]
	v_lshl_add_u64 v[106:107], s[4:5], 0, v[100:101]
	v_pk_fma_f32 v[94:95], v[96:97], v[114:115], v[94:95] neg_lo:[0,0,1] neg_hi:[0,0,1]
	v_pk_mul_f32 v[92:93], v[92:93], v[114:115]
	v_cndmask_b32_e32 v99, 0, v234, vcc
	v_lshl_add_u64 v[106:107], v[106:107], 0, s[12:13]
	v_pk_fma_f32 v[92:93], v[96:97], v[112:113], v[92:93]
	v_pk_mul_f32 v[96:97], v[108:109], v[104:105] op_sel_hi:[1,0]
	v_pk_mul_f32 v[110:111], v[104:105], v[94:95] op_sel_hi:[0,1]
	v_ldexp_f32 v98, v98, v99
	v_lshl_add_u64 v[106:107], v[106:107], 0, v[32:33]
	v_cvt_pk_bf16_f32 v96, v96, v97
	v_cvt_pk_bf16_f32 v97, v110, v111
	v_mul_f32_e32 v98, 0x3e000000, v98
	global_store_dwordx2 v[106:107], v[96:97], off
	v_pk_mul_f32 v[96:97], v[90:91], v[104:105] op_sel_hi:[1,0]
	v_pk_mul_f32 v[110:111], v[104:105], v[92:93] op_sel_hi:[0,1]
	v_cndmask_b32_e64 v98, v98, 0, s[0:1]
	v_lshl_add_u64 v[100:101], v[142:143], 0, v[100:101]
	v_cvt_pk_bf16_f32 v96, v96, v97
	v_cvt_pk_bf16_f32 v97, v110, v111
	s_and_b64 vcc, exec, s[40:41]
	global_store_dwordx2 v[106:107], v[96:97], off offset:64
	s_cbranch_vccnz .LBB0_328
	v_pk_mul_f32 v[96:97], v[108:109], v[98:99] op_sel_hi:[1,0]
	v_pk_mul_f32 v[94:95], v[94:95], v[98:99] op_sel_hi:[1,0]
	v_pk_mul_f32 v[90:91], v[90:91], v[98:99] op_sel_hi:[1,0]
	v_pk_mul_f32 v[92:93], v[92:93], v[98:99] op_sel_hi:[1,0]
	v_cvt_pk_bf16_f32 v96, v96, v97
	v_cvt_pk_bf16_f32 v97, v94, v95
	v_cvt_pk_bf16_f32 v90, v90, v91
	v_cvt_pk_bf16_f32 v91, v92, v93
	global_store_dwordx2 v[100:101], v[96:97], off
	global_store_dwordx2 v[100:101], v[90:91], off offset:64
.LBB0_328:
	v_mov_b32_e32 v105, v104
	s_and_b64 vcc, exec, s[40:41]
	s_waitcnt vmcnt(2)
	v_mov_b32_e32 v97, v182
	v_mov_b32_e32 v182, v181
	v_mov_b32_e32 v96, v180
	v_pk_mul_f32 v[90:91], v[82:83], v[182:183]
	v_pk_mul_f32 v[82:83], v[82:83], v[96:97]
	v_pk_fma_f32 v[90:91], v[86:87], v[96:97], v[90:91] neg_lo:[0,0,1] neg_hi:[0,0,1]
	v_mov_b32_e32 v97, v178
	v_mov_b32_e32 v178, v177
	v_pk_fma_f32 v[82:83], v[86:87], v[182:183], v[82:83]
	v_mov_b32_e32 v96, v176
	v_pk_mul_f32 v[86:87], v[84:85], v[178:179]
	v_pk_mul_f32 v[84:85], v[84:85], v[96:97]
	v_pk_fma_f32 v[86:87], v[88:89], v[96:97], v[86:87] neg_lo:[0,0,1] neg_hi:[0,0,1]
	v_pk_fma_f32 v[84:85], v[88:89], v[178:179], v[84:85]
	v_pk_mul_f32 v[88:89], v[104:105], v[90:91]
	v_pk_mul_f32 v[176:177], v[104:105], v[86:87]
	v_cvt_pk_bf16_f32 v88, v88, v89
	v_cvt_pk_bf16_f32 v89, v176, v177
	global_store_dwordx2 v[106:107], v[88:89], off offset:8
	v_pk_mul_f32 v[88:89], v[104:105], v[82:83]
	v_pk_mul_f32 v[176:177], v[104:105], v[84:85]
	v_cvt_pk_bf16_f32 v88, v88, v89
	v_cvt_pk_bf16_f32 v89, v176, v177
	global_store_dwordx2 v[106:107], v[88:89], off offset:72
	s_cbranch_vccnz .LBB0_330
	v_pk_mul_f32 v[88:89], v[98:99], v[90:91] op_sel_hi:[0,1]
	v_pk_mul_f32 v[86:87], v[98:99], v[86:87] op_sel_hi:[0,1]
	v_pk_mul_f32 v[82:83], v[98:99], v[82:83] op_sel_hi:[0,1]
	v_pk_mul_f32 v[84:85], v[98:99], v[84:85] op_sel_hi:[0,1]
	v_cvt_pk_bf16_f32 v88, v88, v89
	v_cvt_pk_bf16_f32 v89, v86, v87
	v_cvt_pk_bf16_f32 v82, v82, v83
	v_cvt_pk_bf16_f32 v83, v84, v85
	global_store_dwordx2 v[100:101], v[88:89], off offset:8
	global_store_dwordx2 v[100:101], v[82:83], off offset:72

; __device__ __forceinline__ unsigned cvt_pk_bf16(float lo, float hi) { const f32x2_cv v = {lo, hi}; const bf16x2_cv b = __builtin_convertvector(v, bf16x2_cv); return __builtin_bit_cast(unsigned, b); }
;     DI void operator()(const f32x4 (&acc)[2][2][4][2], const Unit& u, int wr, int wc, int fr, int fq) const {
;     ...
;                     int pos, jc, L; row_info(g, row, pos, jc, L);
;                     const f32x4* rp = (const f32x4*)(rot + ((size_t)pos * 32 + 8 * fq) * 2);
;                     const float e1 = exp2f((float)(jc + 1) * lg);
;                     const float sa = pn == 0 ? e1 : 0.125f / e1, sb = (g == 0 && row >= 8720) ? 0.f : 0.125f * exp2f((float)(L - 1 - jc) * lg);
;                     bf16_t* d0 = gb + (size_t)(pn == 0 ? CP_QINR : CP_KINR) * G0ROWS + (size_t)row * 256 + wc * 64 + 8 * fq;
;                     bf16_t* d1 = gb + (size_t)CP_KSTR * G0ROWS + (size_t)row * 256 + wc * 64 + 8 * fq;
; #pragma unroll
;                     for (int n = 0; n < 2; ++n) {
;                         const f32x4 cs0 = rp[2 * n], cs1 = rp[2 * n + 1];
;                         const f32x4 x1 = acc[ai][0][m][n], x2 = acc[ai][1][m][n];
;                         f32x4 o1, o2;
;                         o1[0] = x1[0] * cs0[0] - x2[0] * cs0[1]; o2[0] = x1[0] * cs0[1] + x2[0] * cs0[0];
;                         o1[1] = x1[1] * cs0[2] - x2[1] * cs0[3]; o2[1] = x1[1] * cs0[3] + x2[1] * cs0[2];
;                         o1[2] = x1[2] * cs1[0] - x2[2] * cs1[1]; o2[2] = x1[2] * cs1[1] + x2[2] * cs1[0];
;                         o1[3] = x1[3] * cs1[2] - x2[3] * cs1[3]; o2[3] = x1[3] * cs1[3] + x2[3] * cs1[2];
;                         u32x2 w; w.x = cvt_pk_bf16(o1[0] * sa, o1[1] * sa); w.y = cvt_pk_bf16(o1[2] * sa, o1[3] * sa); *(u32x2*)(d0 + 4 * n) = w;
;                         w.x = cvt_pk_bf16(o2[0] * sa, o2[1] * sa); w.y = cvt_pk_bf16(o2[2] * sa, o2[3] * sa); *(u32x2*)(d0 + 32 + 4 * n) = w;
;                         if (pn == 1) {
;                             w.x = cvt_pk_bf16(o1[0] * sb, o1[1] * sb); w.y = cvt_pk_bf16(o1[2] * sb, o1[3] * sb); *(u32x2*)(d1 + 4 * n) = w;
;                             w.x = cvt_pk_bf16(o2[0] * sb, o2[1] * sb); w.y = cvt_pk_bf16(o2[2] * sb, o2[3] * sb); *(u32x2*)(d1 + 32 + 4 * n) = w;
;                         }
.LBB0_336:
	s_andn2_saveexec_b64 s[6:7], s[6:7]
	v_and_b32_e32 v82, 0x7ff, v84
	v_add_u32_e32 v82, 16, v82
	v_and_b32_e32 v85, 63, v84
	v_mov_b32_e32 v89, 64
	s_or_b64 exec, exec, s[6:7]
	v_mov_b32_e32 v83, v33
	v_lshlrev_b64 v[82:83], 8, v[82:83]
	v_lshl_add_u64 v[86:87], v[140:141], 0, v[82:83]
	global_load_dwordx4 v[94:97], v[86:87], off offset:16
	global_load_dwordx4 v[98:101], v[86:87], off
	global_load_dwordx4 v[176:179], v[86:87], off offset:48
	global_load_dwordx4 v[180:183], v[86:87], off offset:32
	v_add_u32_e32 v82, 1, v85
	v_cvt_f32_u32_e32 v82, v82
	v_mul_f32_e32 v83, v161, v82
	v_cmp_gt_f32_e32 vcc, s22, v83
	s_waitcnt vmcnt(2)
	v_mov_b32_e32 v102, v98
	v_cndmask_b32_e32 v83, 0, v232, vcc
	v_fmac_f32_e32 v83, v161, v82
	v_exp_f32_e32 v82, v83
	v_cndmask_b32_e32 v83, 0, v234, vcc
	v_mov_b32_e32 v103, v100
	v_mov_b32_e32 v100, v99
	v_ldexp_f32 v82, v82, v83
	v_div_scale_f32 v83, s[0:1], v82, v82, s80
	v_rcp_f32_e32 v88, v83
	v_mov_b32_e32 v99, v96
	v_mov_b32_e32 v96, v95
	v_mov_b32_e32 v98, v94
	v_fma_f32 v90, -v83, v88, 1.0
	v_fmac_f32_e32 v88, v90, v88
	v_div_scale_f32 v90, vcc, s80, v82, s80
	v_mul_f32_e32 v91, v90, v88
	v_fma_f32 v92, -v83, v91, v90
	v_fmac_f32_e32 v91, v92, v88
	v_fma_f32 v83, -v83, v91, v90
	v_div_fmas_f32 v83, v83, v88, v91
	v_div_fixup_f32 v83, v83, v82, s80
	v_cndmask_b32_e64 v88, v83, v82, s[42:43]
	v_xad_u32 v82, v85, -1, v89
	v_cvt_f32_i32_e32 v82, v82
	v_cmp_lt_i32_e32 vcc, s24, v84
	s_and_b64 s[0:1], s[44:45], vcc
	v_ashrrev_i32_e32 v85, 31, v84
	v_mul_f32_e32 v83, v161, v82
	v_cmp_gt_f32_e32 vcc, s22, v83
	v_pk_mul_f32 v[92:93], v[74:75], v[100:101]
	v_pk_mul_f32 v[74:75], v[74:75], v[102:103]
	v_cndmask_b32_e32 v83, 0, v232, vcc
	v_fmac_f32_e32 v83, v161, v82
	v_exp_f32_e32 v82, v83
	v_lshlrev_b64 v[84:85], 9, v[84:85]
	v_pk_fma_f32 v[92:93], v[78:79], v[102:103], v[92:93] neg_lo:[0,0,1] neg_hi:[0,0,1]
	v_pk_fma_f32 v[74:75], v[78:79], v[100:101], v[74:75]
	v_pk_mul_f32 v[78:79], v[76:77], v[96:97]
	v_lshl_add_u64 v[90:91], s[4:5], 0, v[84:85]
	v_pk_fma_f32 v[78:79], v[80:81], v[98:99], v[78:79] neg_lo:[0,0,1] neg_hi:[0,0,1]
	v_pk_mul_f32 v[76:77], v[76:77], v[98:99]
	v_cndmask_b32_e32 v83, 0, v234, vcc
	v_lshl_add_u64 v[90:91], v[90:91], 0, s[12:13]
	v_pk_fma_f32 v[76:77], v[80:81], v[96:97], v[76:77]
	v_pk_mul_f32 v[80:81], v[92:93], v[88:89] op_sel_hi:[1,0]
	v_pk_mul_f32 v[94:95], v[88:89], v[78:79] op_sel_hi:[0,1]
	v_ldexp_f32 v82, v82, v83
	v_lshl_add_u64 v[90:91], v[90:91], 0, v[32:33]
	v_cvt_pk_bf16_f32 v80, v80, v81
	v_cvt_pk_bf16_f32 v81, v94, v95
	v_mul_f32_e32 v82, 0x3e000000, v82
	global_store_dwordx2 v[90:91], v[80:81], off
	v_pk_mul_f32 v[80:81], v[74:75], v[88:89] op_sel_hi:[1,0]
	v_pk_mul_f32 v[94:95], v[88:89], v[76:77] op_sel_hi:[0,1]
	v_cndmask_b32_e64 v82, v82, 0, s[0:1]
	v_lshl_add_u64 v[84:85], v[142:143], 0, v[84:85]
	v_cvt_pk_bf16_f32 v80, v80, v81
	v_cvt_pk_bf16_f32 v81, v94, v95
	s_and_b64 vcc, exec, s[40:41]
	global_store_dwordx2 v[90:91], v[80:81], off offset:64
	s_cbranch_vccnz .LBB0_340
	v_pk_mul_f32 v[80:81], v[92:93], v[82:83] op_sel_hi:[1,0]
	v_pk_mul_f32 v[78:79], v[78:79], v[82:83] op_sel_hi:[1,0]
	v_pk_mul_f32 v[74:75], v[74:75], v[82:83] op_sel_hi:[1,0]
	v_pk_mul_f32 v[76:77], v[76:77], v[82:83] op_sel_hi:[1,0]
	v_cvt_pk_bf16_f32 v80, v80, v81
	v_cvt_pk_bf16_f32 v81, v78, v79
	v_cvt_pk_bf16_f32 v74, v74, v75
	v_cvt_pk_bf16_f32 v75, v76, v77
	global_store_dwordx2 v[84:85], v[80:81], off
	global_store_dwordx2 v[84:85], v[74:75], off offset:64
.LBB0_340:
	v_mov_b32_e32 v89, v88
	s_and_b64 vcc, exec, s[40:41]
	s_waitcnt vmcnt(2)
	v_mov_b32_e32 v81, v182
	v_mov_b32_e32 v182, v181
	v_mov_b32_e32 v80, v180
	v_pk_mul_f32 v[74:75], v[66:67], v[182:183]
	v_pk_mul_f32 v[66:67], v[66:67], v[80:81]
	v_pk_fma_f32 v[74:75], v[70:71], v[80:81], v[74:75] neg_lo:[0,0,1] neg_hi:[0,0,1]
	v_mov_b32_e32 v81, v178
	v_mov_b32_e32 v178, v177
	v_pk_fma_f32 v[66:67], v[70:71], v[182:183], v[66:67]
	v_mov_b32_e32 v80, v176
	v_pk_mul_f32 v[70:71], v[68:69], v[178:179]
	v_pk_mul_f32 v[68:69], v[68:69], v[80:81]
	v_pk_fma_f32 v[70:71], v[72:73], v[80:81], v[70:71] neg_lo:[0,0,1] neg_hi:[0,0,1]
	v_pk_fma_f32 v[68:69], v[72:73], v[178:179], v[68:69]
	v_pk_mul_f32 v[72:73], v[88:89], v[74:75]
	v_pk_mul_f32 v[176:177], v[88:89], v[70:71]
	v_cvt_pk_bf16_f32 v72, v72, v73
	v_cvt_pk_bf16_f32 v73, v176, v177
	global_store_dwordx2 v[90:91], v[72:73], off offset:8
	v_pk_mul_f32 v[72:73], v[88:89], v[66:67]
	v_pk_mul_f32 v[176:177], v[88:89], v[68:69]
	v_cvt_pk_bf16_f32 v72, v72, v73
	v_cvt_pk_bf16_f32 v73, v176, v177
	global_store_dwordx2 v[90:91], v[72:73], off offset:72
	s_cbranch_vccnz .LBB0_342
	v_pk_mul_f32 v[72:73], v[82:83], v[74:75] op_sel_hi:[0,1]
	v_pk_mul_f32 v[70:71], v[82:83], v[70:71] op_sel_hi:[0,1]
	v_pk_mul_f32 v[66:67], v[82:83], v[66:67] op_sel_hi:[0,1]
	v_pk_mul_f32 v[68:69], v[82:83], v[68:69] op_sel_hi:[0,1]
	v_cvt_pk_bf16_f32 v72, v72, v73
	v_cvt_pk_bf16_f32 v73, v70, v71
	v_cvt_pk_bf16_f32 v66, v66, v67
	v_cvt_pk_bf16_f32 v67, v68, v69
	global_store_dwordx2 v[84:85], v[72:73], off offset:8
	global_store_dwordx2 v[84:85], v[66:67], off offset:72

; __device__ __forceinline__ unsigned cvt_pk_bf16(float lo, float hi) { const f32x2_cv v = {lo, hi}; const bf16x2_cv b = __builtin_convertvector(v, bf16x2_cv); return __builtin_bit_cast(unsigned, b); }
;     DI void operator()(const f32x4 (&acc)[2][2][4][2], const Unit& u, int wr, int wc, int fr, int fq) const {
;     ...
;                     int pos, jc, L; row_info(g, row, pos, jc, L);
;                     const f32x4* rp = (const f32x4*)(rot + ((size_t)pos * 32 + 8 * fq) * 2);
;                     const float e1 = exp2f((float)(jc + 1) * lg);
;                     const float sa = pn == 0 ? e1 : 0.125f / e1, sb = (g == 0 && row >= 8720) ? 0.f : 0.125f * exp2f((float)(L - 1 - jc) * lg);
;                     bf16_t* d0 = gb + (size_t)(pn == 0 ? CP_QINR : CP_KINR) * G0ROWS + (size_t)row * 256 + wc * 64 + 8 * fq;
;                     bf16_t* d1 = gb + (size_t)CP_KSTR * G0ROWS + (size_t)row * 256 + wc * 64 + 8 * fq;
; #pragma unroll
;                     for (int n = 0; n < 2; ++n) {
;                         const f32x4 cs0 = rp[2 * n], cs1 = rp[2 * n + 1];
;                         const f32x4 x1 = acc[ai][0][m][n], x2 = acc[ai][1][m][n];
;                         f32x4 o1, o2;
;                         o1[0] = x1[0] * cs0[0] - x2[0] * cs0[1]; o2[0] = x1[0] * cs0[1] + x2[0] * cs0[0];
;                         o1[1] = x1[1] * cs0[2] - x2[1] * cs0[3]; o2[1] = x1[1] * cs0[3] + x2[1] * cs0[2];
;                         o1[2] = x1[2] * cs1[0] - x2[2] * cs1[1]; o2[2] = x1[2] * cs1[1] + x2[2] * cs1[0];
;                         o1[3] = x1[3] * cs1[2] - x2[3] * cs1[3]; o2[3] = x1[3] * cs1[3] + x2[3] * cs1[2];
;                         u32x2 w; w.x = cvt_pk_bf16(o1[0] * sa, o1[1] * sa); w.y = cvt_pk_bf16(o1[2] * sa, o1[3] * sa); *(u32x2*)(d0 + 4 * n) = w;
;                         w.x = cvt_pk_bf16(o2[0] * sa, o2[1] * sa); w.y = cvt_pk_bf16(o2[2] * sa, o2[3] * sa); *(u32x2*)(d0 + 32 + 4 * n) = w;
;                         if (pn == 1) {
;                             w.x = cvt_pk_bf16(o1[0] * sb, o1[1] * sb); w.y = cvt_pk_bf16(o1[2] * sb, o1[3] * sb); *(u32x2*)(d1 + 4 * n) = w;
;                             w.x = cvt_pk_bf16(o2[0] * sb, o2[1] * sb); w.y = cvt_pk_bf16(o2[2] * sb, o2[3] * sb); *(u32x2*)(d1 + 32 + 4 * n) = w;
;                         }
.LBB0_348:
	s_andn2_saveexec_b64 s[6:7], s[6:7]
	v_and_b32_e32 v66, 0x7ff, v68
	v_add_u32_e32 v66, 16, v66
	v_and_b32_e32 v69, 63, v68
	v_mov_b32_e32 v73, 64
	s_or_b64 exec, exec, s[6:7]
	v_mov_b32_e32 v67, v33
	v_lshlrev_b64 v[66:67], 8, v[66:67]
	v_lshl_add_u64 v[70:71], v[140:141], 0, v[66:67]
	global_load_dwordx4 v[78:81], v[70:71], off offset:16
	global_load_dwordx4 v[82:85], v[70:71], off
	global_load_dwordx4 v[176:179], v[70:71], off offset:48
	global_load_dwordx4 v[180:183], v[70:71], off offset:32
	v_add_u32_e32 v66, 1, v69
	v_cvt_f32_u32_e32 v66, v66
	v_mul_f32_e32 v67, v161, v66
	v_cmp_gt_f32_e32 vcc, s22, v67
	s_waitcnt vmcnt(2)
	v_mov_b32_e32 v86, v82
	v_cndmask_b32_e32 v67, 0, v232, vcc
	v_fmac_f32_e32 v67, v161, v66
	v_exp_f32_e32 v66, v67
	v_cndmask_b32_e32 v67, 0, v234, vcc
	v_mov_b32_e32 v87, v84
	v_mov_b32_e32 v84, v83
	v_ldexp_f32 v66, v66, v67
	v_div_scale_f32 v67, s[0:1], v66, v66, s80
	v_rcp_f32_e32 v72, v67
	v_mov_b32_e32 v83, v80
	v_mov_b32_e32 v80, v79
	v_mov_b32_e32 v82, v78
	v_fma_f32 v74, -v67, v72, 1.0
	v_fmac_f32_e32 v72, v74, v72
	v_div_scale_f32 v74, vcc, s80, v66, s80
	v_mul_f32_e32 v75, v74, v72
	v_fma_f32 v76, -v67, v75, v74
	v_fmac_f32_e32 v75, v76, v72
	v_fma_f32 v67, -v67, v75, v74
	v_div_fmas_f32 v67, v67, v72, v75
	v_div_fixup_f32 v67, v67, v66, s80
	v_cndmask_b32_e64 v72, v67, v66, s[42:43]
	v_xad_u32 v66, v69, -1, v73
	v_cvt_f32_i32_e32 v66, v66
	v_cmp_lt_i32_e32 vcc, s24, v68
	s_and_b64 s[0:1], s[44:45], vcc
	v_ashrrev_i32_e32 v69, 31, v68
	v_mul_f32_e32 v67, v161, v66
	v_cmp_gt_f32_e32 vcc, s22, v67
	v_pk_mul_f32 v[76:77], v[58:59], v[84:85]
	v_pk_mul_f32 v[58:59], v[58:59], v[86:87]
	v_cndmask_b32_e32 v67, 0, v232, vcc
	v_fmac_f32_e32 v67, v161, v66
	v_exp_f32_e32 v66, v67
	v_lshlrev_b64 v[68:69], 9, v[68:69]
	v_pk_fma_f32 v[76:77], v[62:63], v[86:87], v[76:77] neg_lo:[0,0,1] neg_hi:[0,0,1]
	v_pk_fma_f32 v[58:59], v[62:63], v[84:85], v[58:59]
	v_pk_mul_f32 v[62:63], v[60:61], v[80:81]
	v_lshl_add_u64 v[74:75], s[4:5], 0, v[68:69]
	v_pk_fma_f32 v[62:63], v[64:65], v[82:83], v[62:63] neg_lo:[0,0,1] neg_hi:[0,0,1]
	v_pk_mul_f32 v[60:61], v[60:61], v[82:83]
	v_cndmask_b32_e32 v67, 0, v234, vcc
	v_lshl_add_u64 v[74:75], v[74:75], 0, s[12:13]
	v_pk_fma_f32 v[60:61], v[64:65], v[80:81], v[60:61]
	v_pk_mul_f32 v[64:65], v[76:77], v[72:73] op_sel_hi:[1,0]
	v_pk_mul_f32 v[78:79], v[72:73], v[62:63] op_sel_hi:[0,1]
	v_ldexp_f32 v66, v66, v67
	v_lshl_add_u64 v[74:75], v[74:75], 0, v[32:33]
	v_cvt_pk_bf16_f32 v64, v64, v65
	v_cvt_pk_bf16_f32 v65, v78, v79
	v_mul_f32_e32 v66, 0x3e000000, v66
	global_store_dwordx2 v[74:75], v[64:65], off
	v_pk_mul_f32 v[64:65], v[58:59], v[72:73] op_sel_hi:[1,0]
	v_pk_mul_f32 v[78:79], v[72:73], v[60:61] op_sel_hi:[0,1]
	v_cndmask_b32_e64 v66, v66, 0, s[0:1]
	v_lshl_add_u64 v[68:69], v[142:143], 0, v[68:69]
	v_cvt_pk_bf16_f32 v64, v64, v65
	v_cvt_pk_bf16_f32 v65, v78, v79
	s_and_b64 vcc, exec, s[40:41]
	global_store_dwordx2 v[74:75], v[64:65], off offset:64
	s_cbranch_vccnz .LBB0_352
	v_pk_mul_f32 v[64:65], v[76:77], v[66:67] op_sel_hi:[1,0]
	v_pk_mul_f32 v[62:63], v[62:63], v[66:67] op_sel_hi:[1,0]
	v_pk_mul_f32 v[58:59], v[58:59], v[66:67] op_sel_hi:[1,0]
	v_pk_mul_f32 v[60:61], v[60:61], v[66:67] op_sel_hi:[1,0]
	v_cvt_pk_bf16_f32 v64, v64, v65
	v_cvt_pk_bf16_f32 v65, v62, v63
	v_cvt_pk_bf16_f32 v58, v58, v59
	v_cvt_pk_bf16_f32 v59, v60, v61
	global_store_dwordx2 v[68:69], v[64:65], off
	global_store_dwordx2 v[68:69], v[58:59], off offset:64
.LBB0_352:
	v_mov_b32_e32 v73, v72
	s_and_b64 vcc, exec, s[40:41]
	s_waitcnt vmcnt(2)
	v_mov_b32_e32 v65, v182
	v_mov_b32_e32 v182, v181
	v_mov_b32_e32 v64, v180
	v_pk_mul_f32 v[58:59], v[50:51], v[182:183]
	v_pk_mul_f32 v[50:51], v[50:51], v[64:65]
	v_pk_fma_f32 v[58:59], v[54:55], v[64:65], v[58:59] neg_lo:[0,0,1] neg_hi:[0,0,1]
	v_mov_b32_e32 v65, v178
	v_mov_b32_e32 v178, v177
	v_pk_fma_f32 v[50:51], v[54:55], v[182:183], v[50:51]
	v_mov_b32_e32 v64, v176
	v_pk_mul_f32 v[54:55], v[52:53], v[178:179]
	v_pk_mul_f32 v[52:53], v[52:53], v[64:65]
	v_pk_fma_f32 v[54:55], v[56:57], v[64:65], v[54:55] neg_lo:[0,0,1] neg_hi:[0,0,1]
	v_pk_fma_f32 v[52:53], v[56:57], v[178:179], v[52:53]
	v_pk_mul_f32 v[56:57], v[72:73], v[58:59]
	v_pk_mul_f32 v[176:177], v[72:73], v[54:55]
	v_cvt_pk_bf16_f32 v56, v56, v57
	v_cvt_pk_bf16_f32 v57, v176, v177
	global_store_dwordx2 v[74:75], v[56:57], off offset:8
	v_pk_mul_f32 v[56:57], v[72:73], v[50:51]
	v_pk_mul_f32 v[176:177], v[72:73], v[52:53]
	v_cvt_pk_bf16_f32 v56, v56, v57
	v_cvt_pk_bf16_f32 v57, v176, v177
	global_store_dwordx2 v[74:75], v[56:57], off offset:72
	s_cbranch_vccnz .LBB0_354
	v_pk_mul_f32 v[56:57], v[66:67], v[58:59] op_sel_hi:[0,1]
	v_pk_mul_f32 v[54:55], v[66:67], v[54:55] op_sel_hi:[0,1]
	v_pk_mul_f32 v[50:51], v[66:67], v[50:51] op_sel_hi:[0,1]
	v_pk_mul_f32 v[52:53], v[66:67], v[52:53] op_sel_hi:[0,1]
	v_cvt_pk_bf16_f32 v56, v56, v57
	v_cvt_pk_bf16_f32 v57, v54, v55
	v_cvt_pk_bf16_f32 v50, v50, v51
	v_cvt_pk_bf16_f32 v51, v52, v53
	global_store_dwordx2 v[68:69], v[56:57], off offset:8
	global_store_dwordx2 v[68:69], v[50:51], off offset:72

; __device__ __forceinline__ unsigned cvt_pk_bf16(float lo, float hi) { const f32x2_cv v = {lo, hi}; const bf16x2_cv b = __builtin_convertvector(v, bf16x2_cv); return __builtin_bit_cast(unsigned, b); }
;     DI void operator()(const f32x4 (&acc)[2][2][4][2], const Unit& u, int wr, int wc, int fr, int fq) const {
;     ...
;                     int pos, jc, L; row_info(g, row, pos, jc, L);
;                     const f32x4* rp = (const f32x4*)(rot + ((size_t)pos * 32 + 8 * fq) * 2);
;                     const float e1 = exp2f((float)(jc + 1) * lg);
;                     const float sa = pn == 0 ? e1 : 0.125f / e1, sb = (g == 0 && row >= 8720) ? 0.f : 0.125f * exp2f((float)(L - 1 - jc) * lg);
;                     bf16_t* d0 = gb + (size_t)(pn == 0 ? CP_QINR : CP_KINR) * G0ROWS + (size_t)row * 256 + wc * 64 + 8 * fq;
;                     bf16_t* d1 = gb + (size_t)CP_KSTR * G0ROWS + (size_t)row * 256 + wc * 64 + 8 * fq;
; #pragma unroll
;                     for (int n = 0; n < 2; ++n) {
;                         const f32x4 cs0 = rp[2 * n], cs1 = rp[2 * n + 1];
;                         const f32x4 x1 = acc[ai][0][m][n], x2 = acc[ai][1][m][n];
;                         f32x4 o1, o2;
;                         o1[0] = x1[0] * cs0[0] - x2[0] * cs0[1]; o2[0] = x1[0] * cs0[1] + x2[0] * cs0[0];
;                         o1[1] = x1[1] * cs0[2] - x2[1] * cs0[3]; o2[1] = x1[1] * cs0[3] + x2[1] * cs0[2];
;                         o1[2] = x1[2] * cs1[0] - x2[2] * cs1[1]; o2[2] = x1[2] * cs1[1] + x2[2] * cs1[0];
;                         o1[3] = x1[3] * cs1[2] - x2[3] * cs1[3]; o2[3] = x1[3] * cs1[3] + x2[3] * cs1[2];
;                         u32x2 w; w.x = cvt_pk_bf16(o1[0] * sa, o1[1] * sa); w.y = cvt_pk_bf16(o1[2] * sa, o1[3] * sa); *(u32x2*)(d0 + 4 * n) = w;
;                         w.x = cvt_pk_bf16(o2[0] * sa, o2[1] * sa); w.y = cvt_pk_bf16(o2[2] * sa, o2[3] * sa); *(u32x2*)(d0 + 32 + 4 * n) = w;
;                         if (pn == 1) {
;                             w.x = cvt_pk_bf16(o1[0] * sb, o1[1] * sb); w.y = cvt_pk_bf16(o1[2] * sb, o1[3] * sb); *(u32x2*)(d1 + 4 * n) = w;
;                             w.x = cvt_pk_bf16(o2[0] * sb, o2[1] * sb); w.y = cvt_pk_bf16(o2[2] * sb, o2[3] * sb); *(u32x2*)(d1 + 32 + 4 * n) = w;
;                         }
.LBB0_360:
	s_andn2_saveexec_b64 s[6:7], s[6:7]
	v_and_b32_e32 v50, 0x7ff, v52
	v_add_u32_e32 v50, 16, v50
	v_and_b32_e32 v53, 63, v52
	v_mov_b32_e32 v57, 64
	s_or_b64 exec, exec, s[6:7]
	v_mov_b32_e32 v51, v33
	v_lshlrev_b64 v[50:51], 8, v[50:51]
	v_lshl_add_u64 v[54:55], v[140:141], 0, v[50:51]
	global_load_dwordx4 v[62:65], v[54:55], off offset:16
	global_load_dwordx4 v[66:69], v[54:55], off
	global_load_dwordx4 v[176:179], v[54:55], off offset:48
	global_load_dwordx4 v[180:183], v[54:55], off offset:32
	v_add_u32_e32 v50, 1, v53
	v_cvt_f32_u32_e32 v50, v50
	v_mul_f32_e32 v51, v161, v50
	v_cmp_gt_f32_e32 vcc, s22, v51
	s_waitcnt vmcnt(2)
	v_mov_b32_e32 v70, v66
	v_cndmask_b32_e32 v51, 0, v232, vcc
	v_fmac_f32_e32 v51, v161, v50
	v_exp_f32_e32 v50, v51
	v_cndmask_b32_e32 v51, 0, v234, vcc
	v_mov_b32_e32 v71, v68
	v_mov_b32_e32 v68, v67
	v_ldexp_f32 v50, v50, v51
	v_div_scale_f32 v51, s[0:1], v50, v50, s80
	v_rcp_f32_e32 v56, v51
	v_mov_b32_e32 v67, v64
	v_mov_b32_e32 v64, v63
	v_mov_b32_e32 v66, v62
	v_fma_f32 v58, -v51, v56, 1.0
	v_fmac_f32_e32 v56, v58, v56
	v_div_scale_f32 v58, vcc, s80, v50, s80
	v_mul_f32_e32 v59, v58, v56
	v_fma_f32 v60, -v51, v59, v58
	v_fmac_f32_e32 v59, v60, v56
	v_fma_f32 v51, -v51, v59, v58
	v_div_fmas_f32 v51, v51, v56, v59
	v_div_fixup_f32 v51, v51, v50, s80
	v_cndmask_b32_e64 v56, v51, v50, s[42:43]
	v_xad_u32 v50, v53, -1, v57
	v_cvt_f32_i32_e32 v50, v50
	v_cmp_lt_i32_e32 vcc, s24, v52
	s_and_b64 s[0:1], s[44:45], vcc
	v_ashrrev_i32_e32 v53, 31, v52
	v_mul_f32_e32 v51, v161, v50
	v_cmp_gt_f32_e32 vcc, s22, v51
	v_pk_mul_f32 v[60:61], v[42:43], v[68:69]
	v_pk_mul_f32 v[42:43], v[42:43], v[70:71]
	v_cndmask_b32_e32 v51, 0, v232, vcc
	v_fmac_f32_e32 v51, v161, v50
	v_exp_f32_e32 v50, v51
	v_lshlrev_b64 v[52:53], 9, v[52:53]
	v_pk_fma_f32 v[60:61], v[46:47], v[70:71], v[60:61] neg_lo:[0,0,1] neg_hi:[0,0,1]
	v_pk_fma_f32 v[42:43], v[46:47], v[68:69], v[42:43]
	v_pk_mul_f32 v[46:47], v[44:45], v[64:65]
	v_lshl_add_u64 v[58:59], s[4:5], 0, v[52:53]
	v_pk_fma_f32 v[46:47], v[48:49], v[66:67], v[46:47] neg_lo:[0,0,1] neg_hi:[0,0,1]
	v_pk_mul_f32 v[44:45], v[44:45], v[66:67]
	v_cndmask_b32_e32 v51, 0, v234, vcc
	v_lshl_add_u64 v[58:59], v[58:59], 0, s[12:13]
	v_pk_fma_f32 v[44:45], v[48:49], v[64:65], v[44:45]
	v_pk_mul_f32 v[48:49], v[60:61], v[56:57] op_sel_hi:[1,0]
	v_pk_mul_f32 v[62:63], v[56:57], v[46:47] op_sel_hi:[0,1]
	v_ldexp_f32 v50, v50, v51
	v_lshl_add_u64 v[58:59], v[58:59], 0, v[32:33]
	v_cvt_pk_bf16_f32 v48, v48, v49
	v_cvt_pk_bf16_f32 v49, v62, v63
	v_mul_f32_e32 v50, 0x3e000000, v50
	global_store_dwordx2 v[58:59], v[48:49], off
	v_pk_mul_f32 v[48:49], v[42:43], v[56:57] op_sel_hi:[1,0]
	v_pk_mul_f32 v[62:63], v[56:57], v[44:45] op_sel_hi:[0,1]
	v_cndmask_b32_e64 v50, v50, 0, s[0:1]
	v_lshl_add_u64 v[52:53], v[142:143], 0, v[52:53]
	v_cvt_pk_bf16_f32 v48, v48, v49
	v_cvt_pk_bf16_f32 v49, v62, v63
	s_and_b64 vcc, exec, s[40:41]
	global_store_dwordx2 v[58:59], v[48:49], off offset:64
	s_cbranch_vccnz .LBB0_364
	v_pk_mul_f32 v[48:49], v[60:61], v[50:51] op_sel_hi:[1,0]
	v_pk_mul_f32 v[46:47], v[46:47], v[50:51] op_sel_hi:[1,0]
	v_pk_mul_f32 v[42:43], v[42:43], v[50:51] op_sel_hi:[1,0]
	v_pk_mul_f32 v[44:45], v[44:45], v[50:51] op_sel_hi:[1,0]
	v_cvt_pk_bf16_f32 v48, v48, v49
	v_cvt_pk_bf16_f32 v49, v46, v47
	v_cvt_pk_bf16_f32 v42, v42, v43
	v_cvt_pk_bf16_f32 v43, v44, v45
	global_store_dwordx2 v[52:53], v[48:49], off
	global_store_dwordx2 v[52:53], v[42:43], off offset:64
.LBB0_364:
	v_mov_b32_e32 v57, v56
	s_and_b64 vcc, exec, s[40:41]
	s_waitcnt vmcnt(2)
	v_mov_b32_e32 v49, v182
	v_mov_b32_e32 v182, v181
	v_mov_b32_e32 v48, v180
	v_pk_mul_f32 v[42:43], v[34:35], v[182:183]
	v_pk_mul_f32 v[34:35], v[34:35], v[48:49]
	v_pk_fma_f32 v[42:43], v[38:39], v[48:49], v[42:43] neg_lo:[0,0,1] neg_hi:[0,0,1]
	v_mov_b32_e32 v49, v178
	v_mov_b32_e32 v178, v177
	v_pk_fma_f32 v[34:35], v[38:39], v[182:183], v[34:35]
	v_mov_b32_e32 v48, v176
	v_pk_mul_f32 v[38:39], v[36:37], v[178:179]
	v_pk_mul_f32 v[36:37], v[36:37], v[48:49]
	v_pk_fma_f32 v[38:39], v[40:41], v[48:49], v[38:39] neg_lo:[0,0,1] neg_hi:[0,0,1]
	v_pk_fma_f32 v[36:37], v[40:41], v[178:179], v[36:37]
	v_pk_mul_f32 v[40:41], v[56:57], v[42:43]
	v_pk_mul_f32 v[176:177], v[56:57], v[38:39]
	v_cvt_pk_bf16_f32 v40, v40, v41
	v_cvt_pk_bf16_f32 v41, v176, v177
	global_store_dwordx2 v[58:59], v[40:41], off offset:8
	v_pk_mul_f32 v[40:41], v[56:57], v[34:35]
	v_pk_mul_f32 v[176:177], v[56:57], v[36:37]
	v_cvt_pk_bf16_f32 v40, v40, v41
	v_cvt_pk_bf16_f32 v41, v176, v177
	global_store_dwordx2 v[58:59], v[40:41], off offset:72
	s_cbranch_vccnz .LBB0_366
	v_pk_mul_f32 v[40:41], v[50:51], v[42:43] op_sel_hi:[0,1]
	v_pk_mul_f32 v[38:39], v[50:51], v[38:39] op_sel_hi:[0,1]
	v_pk_mul_f32 v[34:35], v[50:51], v[34:35] op_sel_hi:[0,1]
	v_pk_mul_f32 v[36:37], v[50:51], v[36:37] op_sel_hi:[0,1]
	v_cvt_pk_bf16_f32 v40, v40, v41
	v_cvt_pk_bf16_f32 v41, v38, v39
	v_cvt_pk_bf16_f32 v34, v34, v35
	v_cvt_pk_bf16_f32 v35, v36, v37
	global_store_dwordx2 v[52:53], v[40:41], off offset:8
	global_store_dwordx2 v[52:53], v[34:35], off offset:72

; __device__ __forceinline__ unsigned cvt_pk_bf16(float lo, float hi) { const f32x2_cv v = {lo, hi}; const bf16x2_cv b = __builtin_convertvector(v, bf16x2_cv); return __builtin_bit_cast(unsigned, b); }
;     DI void operator()(const f32x4 (&acc)[2][2][4][2], const Unit& u, int wr, int wc, int fr, int fq) const {
;     ...
;                     int pos, jc, L; row_info(g, row, pos, jc, L);
;                     const f32x4* rp = (const f32x4*)(rot + ((size_t)pos * 32 + 8 * fq) * 2);
;                     const float e1 = exp2f((float)(jc + 1) * lg);
;                     const float sa = pn == 0 ? e1 : 0.125f / e1, sb = (g == 0 && row >= 8720) ? 0.f : 0.125f * exp2f((float)(L - 1 - jc) * lg);
;                     bf16_t* d0 = gb + (size_t)(pn == 0 ? CP_QINR : CP_KINR) * G0ROWS + (size_t)row * 256 + wc * 64 + 8 * fq;
;                     bf16_t* d1 = gb + (size_t)CP_KSTR * G0ROWS + (size_t)row * 256 + wc * 64 + 8 * fq;
; #pragma unroll
;                     for (int n = 0; n < 2; ++n) {
;                         const f32x4 cs0 = rp[2 * n], cs1 = rp[2 * n + 1];
;                         const f32x4 x1 = acc[ai][0][m][n], x2 = acc[ai][1][m][n];
;                         f32x4 o1, o2;
;                         o1[0] = x1[0] * cs0[0] - x2[0] * cs0[1]; o2[0] = x1[0] * cs0[1] + x2[0] * cs0[0];
;                         o1[1] = x1[1] * cs0[2] - x2[1] * cs0[3]; o2[1] = x1[1] * cs0[3] + x2[1] * cs0[2];
;                         o1[2] = x1[2] * cs1[0] - x2[2] * cs1[1]; o2[2] = x1[2] * cs1[1] + x2[2] * cs1[0];
;                         o1[3] = x1[3] * cs1[2] - x2[3] * cs1[3]; o2[3] = x1[3] * cs1[3] + x2[3] * cs1[2];
;                         u32x2 w; w.x = cvt_pk_bf16(o1[0] * sa, o1[1] * sa); w.y = cvt_pk_bf16(o1[2] * sa, o1[3] * sa); *(u32x2*)(d0 + 4 * n) = w;
;                         w.x = cvt_pk_bf16(o2[0] * sa, o2[1] * sa); w.y = cvt_pk_bf16(o2[2] * sa, o2[3] * sa); *(u32x2*)(d0 + 32 + 4 * n) = w;
;                         if (pn == 1) {
;                             w.x = cvt_pk_bf16(o1[0] * sb, o1[1] * sb); w.y = cvt_pk_bf16(o1[2] * sb, o1[3] * sb); *(u32x2*)(d1 + 4 * n) = w;
;                             w.x = cvt_pk_bf16(o2[0] * sb, o2[1] * sb); w.y = cvt_pk_bf16(o2[2] * sb, o2[3] * sb); *(u32x2*)(d1 + 32 + 4 * n) = w;
;                         }
.LBB0_372:
	s_andn2_saveexec_b64 s[6:7], s[6:7]
	v_and_b32_e32 v34, 0x7ff, v36
	v_add_u32_e32 v34, 16, v34
	v_and_b32_e32 v37, 63, v36
	v_mov_b32_e32 v41, 64
	s_or_b64 exec, exec, s[6:7]
	v_mov_b32_e32 v35, v33
	v_lshlrev_b64 v[34:35], 8, v[34:35]
	v_lshl_add_u64 v[38:39], v[140:141], 0, v[34:35]
	global_load_dwordx4 v[46:49], v[38:39], off offset:16
	global_load_dwordx4 v[50:53], v[38:39], off
	global_load_dwordx4 v[176:179], v[38:39], off offset:48
	global_load_dwordx4 v[180:183], v[38:39], off offset:32
	v_add_u32_e32 v34, 1, v37
	v_cvt_f32_u32_e32 v34, v34
	v_mul_f32_e32 v35, v161, v34
	v_cmp_gt_f32_e32 vcc, s22, v35
	s_waitcnt vmcnt(2)
	v_mov_b32_e32 v54, v50
	v_cndmask_b32_e32 v35, 0, v232, vcc
	v_fmac_f32_e32 v35, v161, v34
	v_exp_f32_e32 v34, v35
	v_cndmask_b32_e32 v35, 0, v234, vcc
	v_mov_b32_e32 v55, v52
	v_mov_b32_e32 v52, v51
	v_ldexp_f32 v34, v34, v35
	v_div_scale_f32 v35, s[0:1], v34, v34, s80
	v_rcp_f32_e32 v40, v35
	v_mov_b32_e32 v51, v48
	v_mov_b32_e32 v48, v47
	v_mov_b32_e32 v50, v46
	v_fma_f32 v42, -v35, v40, 1.0
	v_fmac_f32_e32 v40, v42, v40
	v_div_scale_f32 v42, vcc, s80, v34, s80
	v_mul_f32_e32 v43, v42, v40
	v_fma_f32 v44, -v35, v43, v42
	v_fmac_f32_e32 v43, v44, v40
	v_fma_f32 v35, -v35, v43, v42
	v_div_fmas_f32 v35, v35, v40, v43
	v_div_fixup_f32 v35, v35, v34, s80
	v_cndmask_b32_e64 v40, v35, v34, s[42:43]
	v_xad_u32 v34, v37, -1, v41
	v_cvt_f32_i32_e32 v34, v34
	v_cmp_lt_i32_e32 vcc, s24, v36
	s_and_b64 s[0:1], s[44:45], vcc
	v_ashrrev_i32_e32 v37, 31, v36
	v_mul_f32_e32 v35, v161, v34
	v_cmp_gt_f32_e32 vcc, s22, v35
	v_pk_mul_f32 v[44:45], v[24:25], v[52:53]
	v_pk_mul_f32 v[24:25], v[24:25], v[54:55]
	v_cndmask_b32_e32 v35, 0, v232, vcc
	v_fmac_f32_e32 v35, v161, v34
	v_exp_f32_e32 v34, v35
	v_lshlrev_b64 v[36:37], 9, v[36:37]
	v_pk_fma_f32 v[44:45], v[28:29], v[54:55], v[44:45] neg_lo:[0,0,1] neg_hi:[0,0,1]
	v_pk_fma_f32 v[24:25], v[28:29], v[52:53], v[24:25]
	v_pk_mul_f32 v[28:29], v[26:27], v[48:49]
	v_lshl_add_u64 v[42:43], s[4:5], 0, v[36:37]
	v_pk_fma_f32 v[28:29], v[30:31], v[50:51], v[28:29] neg_lo:[0,0,1] neg_hi:[0,0,1]
	v_pk_mul_f32 v[26:27], v[26:27], v[50:51]
	v_cndmask_b32_e32 v35, 0, v234, vcc
	v_lshl_add_u64 v[42:43], v[42:43], 0, s[12:13]
	v_pk_fma_f32 v[26:27], v[30:31], v[48:49], v[26:27]
	v_pk_mul_f32 v[30:31], v[44:45], v[40:41] op_sel_hi:[1,0]
	v_pk_mul_f32 v[46:47], v[40:41], v[28:29] op_sel_hi:[0,1]
	v_ldexp_f32 v34, v34, v35
	v_lshl_add_u64 v[42:43], v[42:43], 0, v[32:33]
	v_cvt_pk_bf16_f32 v30, v30, v31
	v_cvt_pk_bf16_f32 v31, v46, v47
	v_mul_f32_e32 v34, 0x3e000000, v34
	global_store_dwordx2 v[42:43], v[30:31], off
	v_pk_mul_f32 v[30:31], v[24:25], v[40:41] op_sel_hi:[1,0]
	v_pk_mul_f32 v[46:47], v[40:41], v[26:27] op_sel_hi:[0,1]
	v_cndmask_b32_e64 v34, v34, 0, s[0:1]
	v_lshl_add_u64 v[36:37], v[142:143], 0, v[36:37]
	v_cvt_pk_bf16_f32 v30, v30, v31
	v_cvt_pk_bf16_f32 v31, v46, v47
	s_and_b64 vcc, exec, s[40:41]
	global_store_dwordx2 v[42:43], v[30:31], off offset:64
	s_cbranch_vccnz .LBB0_376
	v_pk_mul_f32 v[30:31], v[44:45], v[34:35] op_sel_hi:[1,0]
	v_pk_mul_f32 v[28:29], v[28:29], v[34:35] op_sel_hi:[1,0]
	v_pk_mul_f32 v[24:25], v[24:25], v[34:35] op_sel_hi:[1,0]
	v_pk_mul_f32 v[26:27], v[26:27], v[34:35] op_sel_hi:[1,0]
	v_cvt_pk_bf16_f32 v30, v30, v31
	v_cvt_pk_bf16_f32 v31, v28, v29
	v_cvt_pk_bf16_f32 v24, v24, v25
	v_cvt_pk_bf16_f32 v25, v26, v27
	global_store_dwordx2 v[36:37], v[30:31], off
	global_store_dwordx2 v[36:37], v[24:25], off offset:64
.LBB0_376:
	v_mov_b32_e32 v41, v40
	s_and_b64 vcc, exec, s[40:41]
	s_waitcnt vmcnt(2)
	v_mov_b32_e32 v31, v182
	v_mov_b32_e32 v182, v181
	v_mov_b32_e32 v30, v180
	v_pk_mul_f32 v[24:25], v[16:17], v[182:183]
	v_pk_mul_f32 v[16:17], v[16:17], v[30:31]
	v_pk_fma_f32 v[24:25], v[20:21], v[30:31], v[24:25] neg_lo:[0,0,1] neg_hi:[0,0,1]
	v_mov_b32_e32 v31, v178
	v_mov_b32_e32 v178, v177
	v_pk_fma_f32 v[16:17], v[20:21], v[182:183], v[16:17]
	v_mov_b32_e32 v30, v176
	v_pk_mul_f32 v[20:21], v[18:19], v[178:179]
	v_pk_mul_f32 v[18:19], v[18:19], v[30:31]
	v_pk_fma_f32 v[20:21], v[22:23], v[30:31], v[20:21] neg_lo:[0,0,1] neg_hi:[0,0,1]
	v_pk_fma_f32 v[18:19], v[22:23], v[178:179], v[18:19]
	v_pk_mul_f32 v[22:23], v[40:41], v[24:25]
	v_pk_mul_f32 v[176:177], v[40:41], v[20:21]
	v_cvt_pk_bf16_f32 v22, v22, v23
	v_cvt_pk_bf16_f32 v23, v176, v177
	global_store_dwordx2 v[42:43], v[22:23], off offset:8
	v_pk_mul_f32 v[22:23], v[40:41], v[16:17]
	v_pk_mul_f32 v[176:177], v[40:41], v[18:19]
	v_cvt_pk_bf16_f32 v22, v22, v23
	v_cvt_pk_bf16_f32 v23, v176, v177
	global_store_dwordx2 v[42:43], v[22:23], off offset:72
	s_cbranch_vccnz .LBB0_378
	v_pk_mul_f32 v[22:23], v[34:35], v[24:25] op_sel_hi:[0,1]
	v_pk_mul_f32 v[20:21], v[34:35], v[20:21] op_sel_hi:[0,1]
	v_pk_mul_f32 v[16:17], v[34:35], v[16:17] op_sel_hi:[0,1]
	v_pk_mul_f32 v[18:19], v[34:35], v[18:19] op_sel_hi:[0,1]
	v_cvt_pk_bf16_f32 v22, v22, v23
	v_cvt_pk_bf16_f32 v23, v20, v21
	v_cvt_pk_bf16_f32 v16, v16, v17
	v_cvt_pk_bf16_f32 v17, v18, v19
	global_store_dwordx2 v[36:37], v[22:23], off offset:8
	global_store_dwordx2 v[36:37], v[16:17], off offset:72

; __device__ __forceinline__ unsigned cvt_pk_bf16(float lo, float hi) { const f32x2_cv v = {lo, hi}; const bf16x2_cv b = __builtin_convertvector(v, bf16x2_cv); return __builtin_bit_cast(unsigned, b); }
;     DI void operator()(const f32x4 (&acc)[2][2][4][2], const Unit& u, int wr, int wc, int fr, int fq) const {
;     ...
;                     int row = rowb + ai * 128 + m * 16; asm volatile("" : "+v"(row));
;                     int pos, jc, L; row_info(g, row, pos, jc, L);
;                     const f32x4* rp = (const f32x4*)(rot + ((size_t)pos * 32 + 8 * fq) * 2);
;                     const float e1 = exp2f((float)(jc + 1) * lg);
;                     const float sa = pn == 0 ? e1 : 0.125f / e1, sb = (g == 0 && row >= 8720) ? 0.f : 0.125f * exp2f((float)(L - 1 - jc) * lg);
;                     bf16_t* d0 = gb + (size_t)(pn == 0 ? CP_QINR : CP_KINR) * G0ROWS + (size_t)row * 256 + wc * 64 + 8 * fq;
;                     bf16_t* d1 = gb + (size_t)CP_KSTR * G0ROWS + (size_t)row * 256 + wc * 64 + 8 * fq;
; #pragma unroll
;                     for (int n = 0; n < 2; ++n) {
;                         const f32x4 cs0 = rp[2 * n], cs1 = rp[2 * n + 1];
;                         const f32x4 x1 = acc[ai][0][m][n], x2 = acc[ai][1][m][n];
;                         f32x4 o1, o2;
;                         o1[0] = x1[0] * cs0[0] - x2[0] * cs0[1]; o2[0] = x1[0] * cs0[1] + x2[0] * cs0[0];
;                         o1[1] = x1[1] * cs0[2] - x2[1] * cs0[3]; o2[1] = x1[1] * cs0[3] + x2[1] * cs0[2];
;                         o1[2] = x1[2] * cs1[0] - x2[2] * cs1[1]; o2[2] = x1[2] * cs1[1] + x2[2] * cs1[0];
;                         o1[3] = x1[3] * cs1[2] - x2[3] * cs1[3]; o2[3] = x1[3] * cs1[3] + x2[3] * cs1[2];
;                         u32x2 w; w.x = cvt_pk_bf16(o1[0] * sa, o1[1] * sa); w.y = cvt_pk_bf16(o1[2] * sa, o1[3] * sa); *(u32x2*)(d0 + 4 * n) = w;
;                         w.x = cvt_pk_bf16(o2[0] * sa, o2[1] * sa); w.y = cvt_pk_bf16(o2[2] * sa, o2[3] * sa); *(u32x2*)(d0 + 32 + 4 * n) = w;
;                         if (pn == 1) {
;                             w.x = cvt_pk_bf16(o1[0] * sb, o1[1] * sb); w.y = cvt_pk_bf16(o1[2] * sb, o1[3] * sb); *(u32x2*)(d1 + 4 * n) = w;
;                             w.x = cvt_pk_bf16(o2[0] * sb, o2[1] * sb); w.y = cvt_pk_bf16(o2[2] * sb, o2[3] * sb); *(u32x2*)(d1 + 32 + 4 * n) = w;
;                         }
;                     }
.LBB0_384:
	s_andn2_saveexec_b64 s[6:7], s[6:7]
	v_and_b32_e32 v16, 0x7ff, v18
	v_add_u32_e32 v16, 16, v16
	v_and_b32_e32 v19, 63, v18
	v_mov_b32_e32 v23, 64
	s_or_b64 exec, exec, s[6:7]
	v_mov_b32_e32 v17, v33
	v_lshlrev_b64 v[16:17], 8, v[16:17]
	v_lshl_add_u64 v[20:21], v[140:141], 0, v[16:17]
	global_load_dwordx4 v[28:31], v[20:21], off offset:16
	global_load_dwordx4 v[34:37], v[20:21], off
	global_load_dwordx4 v[176:179], v[20:21], off offset:48
	global_load_dwordx4 v[180:183], v[20:21], off offset:32
	v_add_u32_e32 v16, 1, v19
	v_cvt_f32_u32_e32 v16, v16
	v_mul_f32_e32 v17, v161, v16
	v_cmp_gt_f32_e32 vcc, s22, v17
	s_waitcnt vmcnt(2)
	v_mov_b32_e32 v38, v34
	v_cndmask_b32_e32 v17, 0, v232, vcc
	v_fmac_f32_e32 v17, v161, v16
	v_exp_f32_e32 v16, v17
	v_cndmask_b32_e32 v17, 0, v234, vcc
	v_mov_b32_e32 v39, v36
	v_mov_b32_e32 v36, v35
	v_ldexp_f32 v16, v16, v17
	v_div_scale_f32 v17, s[0:1], v16, v16, s80
	v_rcp_f32_e32 v22, v17
	v_mov_b32_e32 v35, v30
	v_mov_b32_e32 v30, v29
	v_mov_b32_e32 v34, v28
	v_fma_f32 v24, -v17, v22, 1.0
	v_fmac_f32_e32 v22, v24, v22
	v_div_scale_f32 v24, vcc, s80, v16, s80
	v_mul_f32_e32 v25, v24, v22
	v_fma_f32 v26, -v17, v25, v24
	v_fmac_f32_e32 v25, v26, v22
	v_fma_f32 v17, -v17, v25, v24
	v_div_fmas_f32 v17, v17, v22, v25
	v_div_fixup_f32 v17, v17, v16, s80
	v_cndmask_b32_e64 v22, v17, v16, s[42:43]
	v_xad_u32 v16, v19, -1, v23
	v_cvt_f32_i32_e32 v16, v16
	v_cmp_lt_i32_e32 vcc, s24, v18
	s_and_b64 s[0:1], s[44:45], vcc
	v_ashrrev_i32_e32 v19, 31, v18
	v_mul_f32_e32 v17, v161, v16
	v_cmp_gt_f32_e32 vcc, s22, v17
	v_pk_mul_f32 v[26:27], v[8:9], v[36:37]
	v_pk_mul_f32 v[8:9], v[8:9], v[38:39]
	v_cndmask_b32_e32 v17, 0, v232, vcc
	v_fmac_f32_e32 v17, v161, v16
	v_exp_f32_e32 v16, v17
	v_lshlrev_b64 v[18:19], 9, v[18:19]
	v_pk_fma_f32 v[26:27], v[12:13], v[38:39], v[26:27] neg_lo:[0,0,1] neg_hi:[0,0,1]
	v_pk_fma_f32 v[8:9], v[12:13], v[36:37], v[8:9]
	v_pk_mul_f32 v[12:13], v[10:11], v[30:31]
	v_lshl_add_u64 v[24:25], s[4:5], 0, v[18:19]
	v_pk_fma_f32 v[12:13], v[14:15], v[34:35], v[12:13] neg_lo:[0,0,1] neg_hi:[0,0,1]
	v_pk_mul_f32 v[10:11], v[10:11], v[34:35]
	v_cndmask_b32_e32 v17, 0, v234, vcc
	v_lshl_add_u64 v[24:25], v[24:25], 0, s[12:13]
	v_pk_fma_f32 v[10:11], v[14:15], v[30:31], v[10:11]
	v_pk_mul_f32 v[14:15], v[26:27], v[22:23] op_sel_hi:[1,0]
	v_pk_mul_f32 v[28:29], v[22:23], v[12:13] op_sel_hi:[0,1]
	v_ldexp_f32 v16, v16, v17
	v_lshl_add_u64 v[24:25], v[24:25], 0, v[32:33]
	v_cvt_pk_bf16_f32 v14, v14, v15
	v_cvt_pk_bf16_f32 v15, v28, v29
	v_mul_f32_e32 v16, 0x3e000000, v16
	global_store_dwordx2 v[24:25], v[14:15], off
	v_pk_mul_f32 v[14:15], v[8:9], v[22:23] op_sel_hi:[1,0]
	v_pk_mul_f32 v[28:29], v[22:23], v[10:11] op_sel_hi:[0,1]
	v_cndmask_b32_e64 v16, v16, 0, s[0:1]
	v_lshl_add_u64 v[18:19], v[142:143], 0, v[18:19]
	v_cvt_pk_bf16_f32 v14, v14, v15
	v_cvt_pk_bf16_f32 v15, v28, v29
	s_and_b64 vcc, exec, s[40:41]
	global_store_dwordx2 v[24:25], v[14:15], off offset:64
	s_cbranch_vccnz .LBB0_388
	v_pk_mul_f32 v[14:15], v[26:27], v[16:17] op_sel_hi:[1,0]
	v_pk_mul_f32 v[12:13], v[12:13], v[16:17] op_sel_hi:[1,0]
	v_pk_mul_f32 v[8:9], v[8:9], v[16:17] op_sel_hi:[1,0]
	v_pk_mul_f32 v[10:11], v[10:11], v[16:17] op_sel_hi:[1,0]
	v_cvt_pk_bf16_f32 v14, v14, v15
	v_cvt_pk_bf16_f32 v15, v12, v13
	v_cvt_pk_bf16_f32 v8, v8, v9
	v_cvt_pk_bf16_f32 v9, v10, v11
	global_store_dwordx2 v[18:19], v[14:15], off
	global_store_dwordx2 v[18:19], v[8:9], off offset:64
.LBB0_388:
	v_mov_b32_e32 v23, v22
	s_and_b64 vcc, exec, s[40:41]
	s_waitcnt vmcnt(2)
	v_mov_b32_e32 v15, v182
	v_mov_b32_e32 v182, v181
	v_mov_b32_e32 v14, v180
	v_pk_mul_f32 v[8:9], v[0:1], v[182:183]
	v_pk_mul_f32 v[0:1], v[0:1], v[14:15]
	v_pk_fma_f32 v[8:9], v[4:5], v[14:15], v[8:9] neg_lo:[0,0,1] neg_hi:[0,0,1]
	v_mov_b32_e32 v15, v178
	v_mov_b32_e32 v178, v177
	v_pk_fma_f32 v[0:1], v[4:5], v[182:183], v[0:1]
	v_mov_b32_e32 v14, v176
	v_pk_mul_f32 v[4:5], v[2:3], v[178:179]
	v_pk_mul_f32 v[2:3], v[2:3], v[14:15]
	v_pk_fma_f32 v[4:5], v[6:7], v[14:15], v[4:5] neg_lo:[0,0,1] neg_hi:[0,0,1]
	v_pk_fma_f32 v[2:3], v[6:7], v[178:179], v[2:3]
	v_pk_mul_f32 v[6:7], v[22:23], v[8:9]
	v_pk_mul_f32 v[176:177], v[22:23], v[4:5]
	v_cvt_pk_bf16_f32 v6, v6, v7
	v_cvt_pk_bf16_f32 v7, v176, v177
	global_store_dwordx2 v[24:25], v[6:7], off offset:8
	v_pk_mul_f32 v[6:7], v[22:23], v[0:1]
	v_pk_mul_f32 v[176:177], v[22:23], v[2:3]
	v_cvt_pk_bf16_f32 v6, v6, v7
	v_cvt_pk_bf16_f32 v7, v176, v177
	global_store_dwordx2 v[24:25], v[6:7], off offset:72
	s_cbranch_vccnz .LBB0_390
	v_pk_mul_f32 v[6:7], v[16:17], v[8:9] op_sel_hi:[0,1]
	v_pk_mul_f32 v[4:5], v[16:17], v[4:5] op_sel_hi:[0,1]
	v_pk_mul_f32 v[0:1], v[16:17], v[0:1] op_sel_hi:[0,1]
	v_pk_mul_f32 v[2:3], v[16:17], v[2:3] op_sel_hi:[0,1]
	v_cvt_pk_bf16_f32 v6, v6, v7
	v_cvt_pk_bf16_f32 v7, v4, v5
	v_cvt_pk_bf16_f32 v0, v0, v1
	v_cvt_pk_bf16_f32 v1, v2, v3
	global_store_dwordx2 v[18:19], v[6:7], off offset:8
	global_store_dwordx2 v[18:19], v[0:1], off offset:72

; __device__ __forceinline__ unsigned cvt_pk_bf16(float lo, float hi) { const f32x2_cv v = {lo, hi}; const bf16x2_cv b = __builtin_convertvector(v, bf16x2_cv); return __builtin_bit_cast(unsigned, b); }
;     DI void operator()(const f32x4 (&acc)[2][2][4][2], const Unit& u, int wr, int wc, int fr, int fq) const {
;     ...
;                     int pos, jc, L; row_info(g, row, pos, jc, L);
;                     const f32x4* rp = (const f32x4*)(rot + ((size_t)pos * 32 + 8 * fq) * 2);
;                     const float e1 = exp2f((float)(jc + 1) * lg);
;                     const float sa = pn == 0 ? e1 : 0.125f / e1, sb = (g == 0 && row >= 8720) ? 0.f : 0.125f * exp2f((float)(L - 1 - jc) * lg);
;                     bf16_t* d0 = gb + (size_t)(pn == 0 ? CP_QINR : CP_KINR) * G0ROWS + (size_t)row * 256 + wc * 64 + 8 * fq;
;                     bf16_t* d1 = gb + (size_t)CP_KSTR * G0ROWS + (size_t)row * 256 + wc * 64 + 8 * fq;
; #pragma unroll
;                     for (int n = 0; n < 2; ++n) {
;                         const f32x4 cs0 = rp[2 * n], cs1 = rp[2 * n + 1];
;                         const f32x4 x1 = acc[ai][0][m][n], x2 = acc[ai][1][m][n];
;                         f32x4 o1, o2;
;                         o1[0] = x1[0] * cs0[0] - x2[0] * cs0[1]; o2[0] = x1[0] * cs0[1] + x2[0] * cs0[0];
;                         o1[1] = x1[1] * cs0[2] - x2[1] * cs0[3]; o2[1] = x1[1] * cs0[3] + x2[1] * cs0[2];
;                         o1[2] = x1[2] * cs1[0] - x2[2] * cs1[1]; o2[2] = x1[2] * cs1[1] + x2[2] * cs1[0];
;                         o1[3] = x1[3] * cs1[2] - x2[3] * cs1[3]; o2[3] = x1[3] * cs1[3] + x2[3] * cs1[2];
;                         u32x2 w; w.x = cvt_pk_bf16(o1[0] * sa, o1[1] * sa); w.y = cvt_pk_bf16(o1[2] * sa, o1[3] * sa); *(u32x2*)(d0 + 4 * n) = w;
;                         w.x = cvt_pk_bf16(o2[0] * sa, o2[1] * sa); w.y = cvt_pk_bf16(o2[2] * sa, o2[3] * sa); *(u32x2*)(d0 + 32 + 4 * n) = w;
;                         if (pn == 1) {
;                             w.x = cvt_pk_bf16(o1[0] * sb, o1[1] * sb); w.y = cvt_pk_bf16(o1[2] * sb, o1[3] * sb); *(u32x2*)(d1 + 4 * n) = w;
;                             w.x = cvt_pk_bf16(o2[0] * sb, o2[1] * sb); w.y = cvt_pk_bf16(o2[2] * sb, o2[3] * sb); *(u32x2*)(d1 + 32 + 4 * n) = w;
;                         }
;                     }
.LBB0_829:
	s_andn2_saveexec_b64 s[4:5], s[4:5]
	v_and_b32_e32 v32, 0x7ff, v148
	v_add_u32_e32 v32, 16, v32
	v_and_b32_e32 v149, 63, v148
	v_mov_b32_e32 v150, 64
	s_or_b64 exec, exec, s[4:5]
	v_lshlrev_b64 v[152:153], 8, v[32:33]
	v_lshl_add_u64 v[152:153], v[140:141], 0, v[152:153]
	global_load_dwordx4 v[164:167], v[152:153], off
	global_load_dwordx4 v[168:171], v[152:153], off offset:16
	global_load_dwordx4 v[176:179], v[152:153], off offset:48
	global_load_dwordx4 v[180:183], v[152:153], off offset:32
	v_add_u32_e32 v151, 1, v149
	v_xad_u32 v150, v149, -1, v150
	v_cvt_f32_u32_e32 v151, v151
	v_cvt_f32_i32_e32 v150, v150
	s_cmp_eq_u32 s40, 0
	s_cselect_b64 s[42:43], -1, 0
	v_mul_f32_e32 v154, v161, v151
	v_mul_f32_e32 v155, v161, v150
	v_cmp_gt_f32_e32 vcc, s22, v154
	v_cmp_gt_f32_e64 s[6:7], s22, v155
	s_and_b64 s[0:1], s[42:43], exec
	v_cndmask_b32_e32 v154, 0, v232, vcc
	v_cndmask_b32_e64 v155, 0, v232, s[6:7]
	v_fmac_f32_e32 v154, v161, v151
	v_fmac_f32_e32 v155, v161, v150
	v_exp_f32_e32 v150, v154
	v_exp_f32_e32 v151, v155
	v_cndmask_b32_e32 v154, 0, v234, vcc
	v_cndmask_b32_e64 v155, 0, v234, s[6:7]
	v_ldexp_f32 v150, v150, v154
	v_div_scale_f32 v154, s[0:1], v150, v150, s80
	v_ldexp_f32 v151, v151, v155
	v_rcp_f32_e32 v155, v154
	v_div_scale_f32 v158, vcc, s80, v150, s80
	v_cmp_lt_i32_e64 s[4:5], s24, v148
	v_fma_f32 v159, -v154, v155, 1.0
	v_fmac_f32_e32 v155, v159, v155
	v_mul_f32_e32 v159, v158, v155
	v_fma_f32 v172, -v154, v159, v158
	v_fmac_f32_e32 v159, v172, v155
	s_cselect_b32 s2, 0, 0x460000
	s_cmp_eq_u32 s40, 1
	v_fma_f32 v154, -v154, v159, v158
	s_cselect_b64 s[6:7], -1, 0
	s_and_b64 s[0:1], s[8:9], s[4:5]
	v_ashrrev_i32_e32 v149, 31, v148
	v_div_fmas_f32 v154, v154, v155, v159
	s_add_u32 s4, s91, s2
	v_lshlrev_b64 v[156:157], 9, v[148:149]
	v_div_fixup_f32 v154, v154, v150, s80
	s_addc_u32 s5, s94, 0
	v_lshl_add_u64 v[148:149], v[142:143], 0, v[156:157]
	v_cndmask_b32_e64 v154, v154, v150, s[42:43]
	s_lshl_b32 s12, s37, 1
	v_lshl_add_u64 v[156:157], s[4:5], 0, v[156:157]
	v_lshlrev_b32_e32 v32, 1, v138
	v_mul_f32_e32 v151, 0x3e000000, v151
	v_lshl_add_u64 v[156:157], v[156:157], 0, s[12:13]
	v_cndmask_b32_e64 v150, v151, 0, s[0:1]
	s_cmp_lg_u32 s40, 1
	v_lshl_add_u64 v[156:157], v[156:157], 0, v[32:33]
	s_waitcnt vmcnt(2)
	v_mov_b32_e32 v158, v164
	v_mov_b32_e32 v159, v166
	v_mov_b32_e32 v166, v165
	v_mov_b32_e32 v165, v170
	v_mov_b32_e32 v170, v169
	v_mov_b32_e32 v164, v168
	v_pk_mul_f32 v[168:169], v[122:123], v[166:167]
	v_pk_mul_f32 v[122:123], v[122:123], v[158:159]
	v_pk_mul_f32 v[172:173], v[124:125], v[170:171]
	v_pk_mul_f32 v[124:125], v[124:125], v[164:165]
	v_pk_fma_f32 v[158:159], v[126:127], v[158:159], v[168:169] neg_lo:[0,0,1] neg_hi:[0,0,1]
	v_pk_fma_f32 v[122:123], v[126:127], v[166:167], v[122:123]
	v_pk_fma_f32 v[126:127], v[128:129], v[164:165], v[172:173] neg_lo:[0,0,1] neg_hi:[0,0,1]
	v_pk_fma_f32 v[124:125], v[128:129], v[170:171], v[124:125]
	v_pk_mul_f32 v[128:129], v[158:159], v[154:155] op_sel_hi:[1,0]
	v_pk_mul_f32 v[164:165], v[154:155], v[126:127] op_sel_hi:[0,1]
	v_pk_mul_f32 v[166:167], v[122:123], v[154:155] op_sel_hi:[1,0]
	v_pk_mul_f32 v[168:169], v[154:155], v[124:125] op_sel_hi:[0,1]
	v_cvt_pk_bf16_f32 v128, v128, v129
	v_cvt_pk_bf16_f32 v129, v164, v165
	v_cvt_pk_bf16_f32 v164, v166, v167
	v_cvt_pk_bf16_f32 v165, v168, v169
	global_store_dwordx2 v[156:157], v[128:129], off
	global_store_dwordx2 v[156:157], v[164:165], off offset:64
	s_cbranch_scc1 .LBB0_833
	v_pk_mul_f32 v[128:129], v[158:159], v[150:151] op_sel_hi:[1,0]
	v_pk_mul_f32 v[126:127], v[126:127], v[150:151] op_sel_hi:[1,0]
	v_pk_mul_f32 v[122:123], v[122:123], v[150:151] op_sel_hi:[1,0]
	v_pk_mul_f32 v[124:125], v[124:125], v[150:151] op_sel_hi:[1,0]
	v_cvt_pk_bf16_f32 v128, v128, v129
	v_cvt_pk_bf16_f32 v129, v126, v127
	v_cvt_pk_bf16_f32 v122, v122, v123
	v_cvt_pk_bf16_f32 v123, v124, v125
	global_store_dwordx2 v[148:149], v[128:129], off
	global_store_dwordx2 v[148:149], v[122:123], off offset:64

; __device__ __forceinline__ unsigned cvt_pk_bf16(float lo, float hi) { const f32x2_cv v = {lo, hi}; const bf16x2_cv b = __builtin_convertvector(v, bf16x2_cv); return __builtin_bit_cast(unsigned, b); }
;     DI void operator()(const f32x4 (&acc)[2][2][4][2], const Unit& u, int wr, int wc, int fr, int fq) const {
;     ...
;                     int pos, jc, L; row_info(g, row, pos, jc, L);
;                     const f32x4* rp = (const f32x4*)(rot + ((size_t)pos * 32 + 8 * fq) * 2);
;                     const float e1 = exp2f((float)(jc + 1) * lg);
;                     const float sa = pn == 0 ? e1 : 0.125f / e1, sb = (g == 0 && row >= 8720) ? 0.f : 0.125f * exp2f((float)(L - 1 - jc) * lg);
;                     bf16_t* d0 = gb + (size_t)(pn == 0 ? CP_QINR : CP_KINR) * G0ROWS + (size_t)row * 256 + wc * 64 + 8 * fq;
;                     bf16_t* d1 = gb + (size_t)CP_KSTR * G0ROWS + (size_t)row * 256 + wc * 64 + 8 * fq;
; #pragma unroll
;                     for (int n = 0; n < 2; ++n) {
;                         const f32x4 cs0 = rp[2 * n], cs1 = rp[2 * n + 1];
;                         const f32x4 x1 = acc[ai][0][m][n], x2 = acc[ai][1][m][n];
;                         f32x4 o1, o2;
;                         o1[0] = x1[0] * cs0[0] - x2[0] * cs0[1]; o2[0] = x1[0] * cs0[1] + x2[0] * cs0[0];
;                         o1[1] = x1[1] * cs0[2] - x2[1] * cs0[3]; o2[1] = x1[1] * cs0[3] + x2[1] * cs0[2];
;                         o1[2] = x1[2] * cs1[0] - x2[2] * cs1[1]; o2[2] = x1[2] * cs1[1] + x2[2] * cs1[0];
;                         o1[3] = x1[3] * cs1[2] - x2[3] * cs1[3]; o2[3] = x1[3] * cs1[3] + x2[3] * cs1[2];
;                         u32x2 w; w.x = cvt_pk_bf16(o1[0] * sa, o1[1] * sa); w.y = cvt_pk_bf16(o1[2] * sa, o1[3] * sa); *(u32x2*)(d0 + 4 * n) = w;
;                         w.x = cvt_pk_bf16(o2[0] * sa, o2[1] * sa); w.y = cvt_pk_bf16(o2[2] * sa, o2[3] * sa); *(u32x2*)(d0 + 32 + 4 * n) = w;
;                         if (pn == 1) {
;                             w.x = cvt_pk_bf16(o1[0] * sb, o1[1] * sb); w.y = cvt_pk_bf16(o1[2] * sb, o1[3] * sb); *(u32x2*)(d1 + 4 * n) = w;
;                             w.x = cvt_pk_bf16(o2[0] * sb, o2[1] * sb); w.y = cvt_pk_bf16(o2[2] * sb, o2[3] * sb); *(u32x2*)(d1 + 32 + 4 * n) = w;
;                         }
;                     }
.LBB0_841:
	s_andn2_saveexec_b64 s[6:7], s[6:7]
	v_and_b32_e32 v114, 0x7ff, v116
	v_add_u32_e32 v114, 16, v114
	v_and_b32_e32 v117, 63, v116
	v_mov_b32_e32 v121, 64
	s_or_b64 exec, exec, s[6:7]
	v_mov_b32_e32 v115, v33
	v_lshlrev_b64 v[114:115], 8, v[114:115]
	v_lshl_add_u64 v[118:119], v[140:141], 0, v[114:115]
	global_load_dwordx4 v[126:129], v[118:119], off offset:16
	global_load_dwordx4 v[148:151], v[118:119], off
	global_load_dwordx4 v[176:179], v[118:119], off offset:48
	global_load_dwordx4 v[180:183], v[118:119], off offset:32
	v_add_u32_e32 v114, 1, v117
	v_cvt_f32_u32_e32 v114, v114
	v_mul_f32_e32 v115, v161, v114
	v_cmp_gt_f32_e32 vcc, s22, v115
	s_waitcnt vmcnt(2)
	v_mov_b32_e32 v152, v148
	v_cndmask_b32_e32 v115, 0, v232, vcc
	v_fmac_f32_e32 v115, v161, v114
	v_exp_f32_e32 v114, v115
	v_cndmask_b32_e32 v115, 0, v234, vcc
	v_mov_b32_e32 v153, v150
	v_mov_b32_e32 v150, v149
	v_ldexp_f32 v114, v114, v115
	v_div_scale_f32 v115, s[0:1], v114, v114, s80
	v_rcp_f32_e32 v120, v115
	v_mov_b32_e32 v149, v128
	v_mov_b32_e32 v128, v127
	v_mov_b32_e32 v148, v126
	v_fma_f32 v122, -v115, v120, 1.0
	v_fmac_f32_e32 v120, v122, v120
	v_div_scale_f32 v122, vcc, s80, v114, s80
	v_mul_f32_e32 v123, v122, v120
	v_fma_f32 v124, -v115, v123, v122
	v_fmac_f32_e32 v123, v124, v120
	v_fma_f32 v115, -v115, v123, v122
	v_div_fmas_f32 v115, v115, v120, v123
	v_div_fixup_f32 v115, v115, v114, s80
	v_cndmask_b32_e64 v120, v115, v114, s[42:43]
	v_xad_u32 v114, v117, -1, v121
	v_cvt_f32_i32_e32 v114, v114
	v_cmp_lt_i32_e32 vcc, s24, v116
	s_and_b64 s[0:1], s[8:9], vcc
	v_ashrrev_i32_e32 v117, 31, v116
	v_mul_f32_e32 v115, v161, v114
	v_cmp_gt_f32_e32 vcc, s22, v115
	v_pk_mul_f32 v[124:125], v[106:107], v[150:151]
	v_pk_mul_f32 v[106:107], v[106:107], v[152:153]
	v_cndmask_b32_e32 v115, 0, v232, vcc
	v_fmac_f32_e32 v115, v161, v114
	v_exp_f32_e32 v114, v115
	v_lshlrev_b64 v[116:117], 9, v[116:117]
	v_pk_fma_f32 v[124:125], v[110:111], v[152:153], v[124:125] neg_lo:[0,0,1] neg_hi:[0,0,1]
	v_pk_fma_f32 v[106:107], v[110:111], v[150:151], v[106:107]
	v_pk_mul_f32 v[110:111], v[108:109], v[128:129]
	v_lshl_add_u64 v[122:123], s[4:5], 0, v[116:117]
	v_pk_fma_f32 v[110:111], v[112:113], v[148:149], v[110:111] neg_lo:[0,0,1] neg_hi:[0,0,1]
	v_pk_mul_f32 v[108:109], v[108:109], v[148:149]
	v_cndmask_b32_e32 v115, 0, v234, vcc
	v_lshl_add_u64 v[122:123], v[122:123], 0, s[12:13]
	v_pk_fma_f32 v[108:109], v[112:113], v[128:129], v[108:109]
	v_pk_mul_f32 v[112:113], v[124:125], v[120:121] op_sel_hi:[1,0]
	v_pk_mul_f32 v[126:127], v[120:121], v[110:111] op_sel_hi:[0,1]
	v_ldexp_f32 v114, v114, v115
	v_lshl_add_u64 v[122:123], v[122:123], 0, v[32:33]
	v_cvt_pk_bf16_f32 v112, v112, v113
	v_cvt_pk_bf16_f32 v113, v126, v127
	v_mul_f32_e32 v114, 0x3e000000, v114
	global_store_dwordx2 v[122:123], v[112:113], off
	v_pk_mul_f32 v[112:113], v[106:107], v[120:121] op_sel_hi:[1,0]
	v_pk_mul_f32 v[126:127], v[120:121], v[108:109] op_sel_hi:[0,1]
	v_cndmask_b32_e64 v114, v114, 0, s[0:1]
	v_lshl_add_u64 v[116:117], v[142:143], 0, v[116:117]
	v_cvt_pk_bf16_f32 v112, v112, v113
	v_cvt_pk_bf16_f32 v113, v126, v127
	s_and_b64 vcc, exec, s[40:41]
	global_store_dwordx2 v[122:123], v[112:113], off offset:64
	s_cbranch_vccnz .LBB0_845
	v_pk_mul_f32 v[112:113], v[124:125], v[114:115] op_sel_hi:[1,0]
	v_pk_mul_f32 v[110:111], v[110:111], v[114:115] op_sel_hi:[1,0]
	v_pk_mul_f32 v[106:107], v[106:107], v[114:115] op_sel_hi:[1,0]
	v_pk_mul_f32 v[108:109], v[108:109], v[114:115] op_sel_hi:[1,0]
	v_cvt_pk_bf16_f32 v112, v112, v113
	v_cvt_pk_bf16_f32 v113, v110, v111
	v_cvt_pk_bf16_f32 v106, v106, v107
	v_cvt_pk_bf16_f32 v107, v108, v109
	global_store_dwordx2 v[116:117], v[112:113], off
	global_store_dwordx2 v[116:117], v[106:107], off offset:64

; __device__ __forceinline__ unsigned cvt_pk_bf16(float lo, float hi) { const f32x2_cv v = {lo, hi}; const bf16x2_cv b = __builtin_convertvector(v, bf16x2_cv); return __builtin_bit_cast(unsigned, b); }
;     DI void operator()(const f32x4 (&acc)[2][2][4][2], const Unit& u, int wr, int wc, int fr, int fq) const {
;     ...
;                     int pos, jc, L; row_info(g, row, pos, jc, L);
;                     const f32x4* rp = (const f32x4*)(rot + ((size_t)pos * 32 + 8 * fq) * 2);
;                     const float e1 = exp2f((float)(jc + 1) * lg);
;                     const float sa = pn == 0 ? e1 : 0.125f / e1, sb = (g == 0 && row >= 8720) ? 0.f : 0.125f * exp2f((float)(L - 1 - jc) * lg);
;                     bf16_t* d0 = gb + (size_t)(pn == 0 ? CP_QINR : CP_KINR) * G0ROWS + (size_t)row * 256 + wc * 64 + 8 * fq;
;                     bf16_t* d1 = gb + (size_t)CP_KSTR * G0ROWS + (size_t)row * 256 + wc * 64 + 8 * fq;
; #pragma unroll
;                     for (int n = 0; n < 2; ++n) {
;                         const f32x4 cs0 = rp[2 * n], cs1 = rp[2 * n + 1];
;                         const f32x4 x1 = acc[ai][0][m][n], x2 = acc[ai][1][m][n];
;                         f32x4 o1, o2;
;                         o1[0] = x1[0] * cs0[0] - x2[0] * cs0[1]; o2[0] = x1[0] * cs0[1] + x2[0] * cs0[0];
;                         o1[1] = x1[1] * cs0[2] - x2[1] * cs0[3]; o2[1] = x1[1] * cs0[3] + x2[1] * cs0[2];
;                         o1[2] = x1[2] * cs1[0] - x2[2] * cs1[1]; o2[2] = x1[2] * cs1[1] + x2[2] * cs1[0];
;                         o1[3] = x1[3] * cs1[2] - x2[3] * cs1[3]; o2[3] = x1[3] * cs1[3] + x2[3] * cs1[2];
;                         u32x2 w; w.x = cvt_pk_bf16(o1[0] * sa, o1[1] * sa); w.y = cvt_pk_bf16(o1[2] * sa, o1[3] * sa); *(u32x2*)(d0 + 4 * n) = w;
;                         w.x = cvt_pk_bf16(o2[0] * sa, o2[1] * sa); w.y = cvt_pk_bf16(o2[2] * sa, o2[3] * sa); *(u32x2*)(d0 + 32 + 4 * n) = w;
;                         if (pn == 1) {
;                             w.x = cvt_pk_bf16(o1[0] * sb, o1[1] * sb); w.y = cvt_pk_bf16(o1[2] * sb, o1[3] * sb); *(u32x2*)(d1 + 4 * n) = w;
;                             w.x = cvt_pk_bf16(o2[0] * sb, o2[1] * sb); w.y = cvt_pk_bf16(o2[2] * sb, o2[3] * sb); *(u32x2*)(d1 + 32 + 4 * n) = w;
;                         }
;                     }
.LBB0_853:
	s_andn2_saveexec_b64 s[6:7], s[6:7]
	v_and_b32_e32 v98, 0x7ff, v100
	v_add_u32_e32 v98, 16, v98
	v_and_b32_e32 v101, 63, v100
	v_mov_b32_e32 v105, 64
	s_or_b64 exec, exec, s[6:7]
	v_mov_b32_e32 v99, v33
	v_lshlrev_b64 v[98:99], 8, v[98:99]
	v_lshl_add_u64 v[102:103], v[140:141], 0, v[98:99]
	global_load_dwordx4 v[110:113], v[102:103], off offset:16
	global_load_dwordx4 v[114:117], v[102:103], off
	global_load_dwordx4 v[176:179], v[102:103], off offset:48
	global_load_dwordx4 v[180:183], v[102:103], off offset:32
	v_add_u32_e32 v98, 1, v101
	v_cvt_f32_u32_e32 v98, v98
	v_mul_f32_e32 v99, v161, v98
	v_cmp_gt_f32_e32 vcc, s22, v99
	s_waitcnt vmcnt(2)
	v_mov_b32_e32 v118, v114
	v_cndmask_b32_e32 v99, 0, v232, vcc
	v_fmac_f32_e32 v99, v161, v98
	v_exp_f32_e32 v98, v99
	v_cndmask_b32_e32 v99, 0, v234, vcc
	v_mov_b32_e32 v119, v116
	v_mov_b32_e32 v116, v115
	v_ldexp_f32 v98, v98, v99
	v_div_scale_f32 v99, s[0:1], v98, v98, s80
	v_rcp_f32_e32 v104, v99
	v_mov_b32_e32 v115, v112
	v_mov_b32_e32 v112, v111
	v_mov_b32_e32 v114, v110
	v_fma_f32 v106, -v99, v104, 1.0
	v_fmac_f32_e32 v104, v106, v104
	v_div_scale_f32 v106, vcc, s80, v98, s80
	v_mul_f32_e32 v107, v106, v104
	v_fma_f32 v108, -v99, v107, v106
	v_fmac_f32_e32 v107, v108, v104
	v_fma_f32 v99, -v99, v107, v106
	v_div_fmas_f32 v99, v99, v104, v107
	v_div_fixup_f32 v99, v99, v98, s80
	v_cndmask_b32_e64 v104, v99, v98, s[42:43]
	v_xad_u32 v98, v101, -1, v105
	v_cvt_f32_i32_e32 v98, v98
	v_cmp_lt_i32_e32 vcc, s24, v100
	s_and_b64 s[0:1], s[8:9], vcc
	v_ashrrev_i32_e32 v101, 31, v100
	v_mul_f32_e32 v99, v161, v98
	v_cmp_gt_f32_e32 vcc, s22, v99
	v_pk_mul_f32 v[108:109], v[90:91], v[116:117]
	v_pk_mul_f32 v[90:91], v[90:91], v[118:119]
	v_cndmask_b32_e32 v99, 0, v232, vcc
	v_fmac_f32_e32 v99, v161, v98
	v_exp_f32_e32 v98, v99
	v_lshlrev_b64 v[100:101], 9, v[100:101]
	v_pk_fma_f32 v[108:109], v[94:95], v[118:119], v[108:109] neg_lo:[0,0,1] neg_hi:[0,0,1]
	v_pk_fma_f32 v[90:91], v[94:95], v[116:117], v[90:91]
	v_pk_mul_f32 v[94:95], v[92:93], v[112:113]
	v_lshl_add_u64 v[106:107], s[4:5], 0, v[100:101]
	v_pk_fma_f32 v[94:95], v[96:97], v[114:115], v[94:95] neg_lo:[0,0,1] neg_hi:[0,0,1]
	v_pk_mul_f32 v[92:93], v[92:93], v[114:115]
	v_cndmask_b32_e32 v99, 0, v234, vcc
	v_lshl_add_u64 v[106:107], v[106:107], 0, s[12:13]
	v_pk_fma_f32 v[92:93], v[96:97], v[112:113], v[92:93]
	v_pk_mul_f32 v[96:97], v[108:109], v[104:105] op_sel_hi:[1,0]
	v_pk_mul_f32 v[110:111], v[104:105], v[94:95] op_sel_hi:[0,1]
	v_ldexp_f32 v98, v98, v99
	v_lshl_add_u64 v[106:107], v[106:107], 0, v[32:33]
	v_cvt_pk_bf16_f32 v96, v96, v97
	v_cvt_pk_bf16_f32 v97, v110, v111
	v_mul_f32_e32 v98, 0x3e000000, v98
	global_store_dwordx2 v[106:107], v[96:97], off
	v_pk_mul_f32 v[96:97], v[90:91], v[104:105] op_sel_hi:[1,0]
	v_pk_mul_f32 v[110:111], v[104:105], v[92:93] op_sel_hi:[0,1]
	v_cndmask_b32_e64 v98, v98, 0, s[0:1]
	v_lshl_add_u64 v[100:101], v[142:143], 0, v[100:101]
	v_cvt_pk_bf16_f32 v96, v96, v97
	v_cvt_pk_bf16_f32 v97, v110, v111
	s_and_b64 vcc, exec, s[40:41]
	global_store_dwordx2 v[106:107], v[96:97], off offset:64
	s_cbranch_vccnz .LBB0_857
	v_pk_mul_f32 v[96:97], v[108:109], v[98:99] op_sel_hi:[1,0]
	v_pk_mul_f32 v[94:95], v[94:95], v[98:99] op_sel_hi:[1,0]
	v_pk_mul_f32 v[90:91], v[90:91], v[98:99] op_sel_hi:[1,0]
	v_pk_mul_f32 v[92:93], v[92:93], v[98:99] op_sel_hi:[1,0]
	v_cvt_pk_bf16_f32 v96, v96, v97
	v_cvt_pk_bf16_f32 v97, v94, v95
	v_cvt_pk_bf16_f32 v90, v90, v91
	v_cvt_pk_bf16_f32 v91, v92, v93
	global_store_dwordx2 v[100:101], v[96:97], off
	global_store_dwordx2 v[100:101], v[90:91], off offset:64

; __device__ __forceinline__ unsigned cvt_pk_bf16(float lo, float hi) { const f32x2_cv v = {lo, hi}; const bf16x2_cv b = __builtin_convertvector(v, bf16x2_cv); return __builtin_bit_cast(unsigned, b); }
;     DI void operator()(const f32x4 (&acc)[2][2][4][2], const Unit& u, int wr, int wc, int fr, int fq) const {
;     ...
;                     int pos, jc, L; row_info(g, row, pos, jc, L);
;                     const f32x4* rp = (const f32x4*)(rot + ((size_t)pos * 32 + 8 * fq) * 2);
;                     const float e1 = exp2f((float)(jc + 1) * lg);
;                     const float sa = pn == 0 ? e1 : 0.125f / e1, sb = (g == 0 && row >= 8720) ? 0.f : 0.125f * exp2f((float)(L - 1 - jc) * lg);
;                     bf16_t* d0 = gb + (size_t)(pn == 0 ? CP_QINR : CP_KINR) * G0ROWS + (size_t)row * 256 + wc * 64 + 8 * fq;
;                     bf16_t* d1 = gb + (size_t)CP_KSTR * G0ROWS + (size_t)row * 256 + wc * 64 + 8 * fq;
; #pragma unroll
;                     for (int n = 0; n < 2; ++n) {
;                         const f32x4 cs0 = rp[2 * n], cs1 = rp[2 * n + 1];
;                         const f32x4 x1 = acc[ai][0][m][n], x2 = acc[ai][1][m][n];
;                         f32x4 o1, o2;
;                         o1[0] = x1[0] * cs0[0] - x2[0] * cs0[1]; o2[0] = x1[0] * cs0[1] + x2[0] * cs0[0];
;                         o1[1] = x1[1] * cs0[2] - x2[1] * cs0[3]; o2[1] = x1[1] * cs0[3] + x2[1] * cs0[2];
;                         o1[2] = x1[2] * cs1[0] - x2[2] * cs1[1]; o2[2] = x1[2] * cs1[1] + x2[2] * cs1[0];
;                         o1[3] = x1[3] * cs1[2] - x2[3] * cs1[3]; o2[3] = x1[3] * cs1[3] + x2[3] * cs1[2];
;                         u32x2 w; w.x = cvt_pk_bf16(o1[0] * sa, o1[1] * sa); w.y = cvt_pk_bf16(o1[2] * sa, o1[3] * sa); *(u32x2*)(d0 + 4 * n) = w;
;                         w.x = cvt_pk_bf16(o2[0] * sa, o2[1] * sa); w.y = cvt_pk_bf16(o2[2] * sa, o2[3] * sa); *(u32x2*)(d0 + 32 + 4 * n) = w;
;                         if (pn == 1) {
;                             w.x = cvt_pk_bf16(o1[0] * sb, o1[1] * sb); w.y = cvt_pk_bf16(o1[2] * sb, o1[3] * sb); *(u32x2*)(d1 + 4 * n) = w;
;                             w.x = cvt_pk_bf16(o2[0] * sb, o2[1] * sb); w.y = cvt_pk_bf16(o2[2] * sb, o2[3] * sb); *(u32x2*)(d1 + 32 + 4 * n) = w;
;                         }
;                     }
.LBB0_865:
	s_andn2_saveexec_b64 s[6:7], s[6:7]
	v_and_b32_e32 v82, 0x7ff, v84
	v_add_u32_e32 v82, 16, v82
	v_and_b32_e32 v85, 63, v84
	v_mov_b32_e32 v89, 64
	s_or_b64 exec, exec, s[6:7]
	v_mov_b32_e32 v83, v33
	v_lshlrev_b64 v[82:83], 8, v[82:83]
	v_lshl_add_u64 v[86:87], v[140:141], 0, v[82:83]
	global_load_dwordx4 v[94:97], v[86:87], off offset:16
	global_load_dwordx4 v[98:101], v[86:87], off
	global_load_dwordx4 v[176:179], v[86:87], off offset:48
	global_load_dwordx4 v[180:183], v[86:87], off offset:32
	v_add_u32_e32 v82, 1, v85
	v_cvt_f32_u32_e32 v82, v82
	v_mul_f32_e32 v83, v161, v82
	v_cmp_gt_f32_e32 vcc, s22, v83
	s_waitcnt vmcnt(2)
	v_mov_b32_e32 v102, v98
	v_cndmask_b32_e32 v83, 0, v232, vcc
	v_fmac_f32_e32 v83, v161, v82
	v_exp_f32_e32 v82, v83
	v_cndmask_b32_e32 v83, 0, v234, vcc
	v_mov_b32_e32 v103, v100
	v_mov_b32_e32 v100, v99
	v_ldexp_f32 v82, v82, v83
	v_div_scale_f32 v83, s[0:1], v82, v82, s80
	v_rcp_f32_e32 v88, v83
	v_mov_b32_e32 v99, v96
	v_mov_b32_e32 v96, v95
	v_mov_b32_e32 v98, v94
	v_fma_f32 v90, -v83, v88, 1.0
	v_fmac_f32_e32 v88, v90, v88
	v_div_scale_f32 v90, vcc, s80, v82, s80
	v_mul_f32_e32 v91, v90, v88
	v_fma_f32 v92, -v83, v91, v90
	v_fmac_f32_e32 v91, v92, v88
	v_fma_f32 v83, -v83, v91, v90
	v_div_fmas_f32 v83, v83, v88, v91
	v_div_fixup_f32 v83, v83, v82, s80
	v_cndmask_b32_e64 v88, v83, v82, s[42:43]
	v_xad_u32 v82, v85, -1, v89
	v_cvt_f32_i32_e32 v82, v82
	v_cmp_lt_i32_e32 vcc, s24, v84
	s_and_b64 s[0:1], s[8:9], vcc
	v_ashrrev_i32_e32 v85, 31, v84
	v_mul_f32_e32 v83, v161, v82
	v_cmp_gt_f32_e32 vcc, s22, v83
	v_pk_mul_f32 v[92:93], v[74:75], v[100:101]
	v_pk_mul_f32 v[74:75], v[74:75], v[102:103]
	v_cndmask_b32_e32 v83, 0, v232, vcc
	v_fmac_f32_e32 v83, v161, v82
	v_exp_f32_e32 v82, v83
	v_lshlrev_b64 v[84:85], 9, v[84:85]
	v_pk_fma_f32 v[92:93], v[78:79], v[102:103], v[92:93] neg_lo:[0,0,1] neg_hi:[0,0,1]
	v_pk_fma_f32 v[74:75], v[78:79], v[100:101], v[74:75]
	v_pk_mul_f32 v[78:79], v[76:77], v[96:97]
	v_lshl_add_u64 v[90:91], s[4:5], 0, v[84:85]
	v_pk_fma_f32 v[78:79], v[80:81], v[98:99], v[78:79] neg_lo:[0,0,1] neg_hi:[0,0,1]
	v_pk_mul_f32 v[76:77], v[76:77], v[98:99]
	v_cndmask_b32_e32 v83, 0, v234, vcc
	v_lshl_add_u64 v[90:91], v[90:91], 0, s[12:13]
	v_pk_fma_f32 v[76:77], v[80:81], v[96:97], v[76:77]
	v_pk_mul_f32 v[80:81], v[92:93], v[88:89] op_sel_hi:[1,0]
	v_pk_mul_f32 v[94:95], v[88:89], v[78:79] op_sel_hi:[0,1]
	v_ldexp_f32 v82, v82, v83
	v_lshl_add_u64 v[90:91], v[90:91], 0, v[32:33]
	v_cvt_pk_bf16_f32 v80, v80, v81
	v_cvt_pk_bf16_f32 v81, v94, v95
	v_mul_f32_e32 v82, 0x3e000000, v82
	global_store_dwordx2 v[90:91], v[80:81], off
	v_pk_mul_f32 v[80:81], v[74:75], v[88:89] op_sel_hi:[1,0]
	v_pk_mul_f32 v[94:95], v[88:89], v[76:77] op_sel_hi:[0,1]
	v_cndmask_b32_e64 v82, v82, 0, s[0:1]
	v_lshl_add_u64 v[84:85], v[142:143], 0, v[84:85]
	v_cvt_pk_bf16_f32 v80, v80, v81
	v_cvt_pk_bf16_f32 v81, v94, v95
	s_and_b64 vcc, exec, s[40:41]
	global_store_dwordx2 v[90:91], v[80:81], off offset:64
	s_cbranch_vccnz .LBB0_869
	v_pk_mul_f32 v[80:81], v[92:93], v[82:83] op_sel_hi:[1,0]
	v_pk_mul_f32 v[78:79], v[78:79], v[82:83] op_sel_hi:[1,0]
	v_pk_mul_f32 v[74:75], v[74:75], v[82:83] op_sel_hi:[1,0]
	v_pk_mul_f32 v[76:77], v[76:77], v[82:83] op_sel_hi:[1,0]
	v_cvt_pk_bf16_f32 v80, v80, v81
	v_cvt_pk_bf16_f32 v81, v78, v79
	v_cvt_pk_bf16_f32 v74, v74, v75
	v_cvt_pk_bf16_f32 v75, v76, v77
	global_store_dwordx2 v[84:85], v[80:81], off
	global_store_dwordx2 v[84:85], v[74:75], off offset:64

; __device__ __forceinline__ unsigned cvt_pk_bf16(float lo, float hi) { const f32x2_cv v = {lo, hi}; const bf16x2_cv b = __builtin_convertvector(v, bf16x2_cv); return __builtin_bit_cast(unsigned, b); }
;     DI void operator()(const f32x4 (&acc)[2][2][4][2], const Unit& u, int wr, int wc, int fr, int fq) const {
;     ...
;                     int pos, jc, L; row_info(g, row, pos, jc, L);
;                     const f32x4* rp = (const f32x4*)(rot + ((size_t)pos * 32 + 8 * fq) * 2);
;                     const float e1 = exp2f((float)(jc + 1) * lg);
;                     const float sa = pn == 0 ? e1 : 0.125f / e1, sb = (g == 0 && row >= 8720) ? 0.f : 0.125f * exp2f((float)(L - 1 - jc) * lg);
;                     bf16_t* d0 = gb + (size_t)(pn == 0 ? CP_QINR : CP_KINR) * G0ROWS + (size_t)row * 256 + wc * 64 + 8 * fq;
;                     bf16_t* d1 = gb + (size_t)CP_KSTR * G0ROWS + (size_t)row * 256 + wc * 64 + 8 * fq;
; #pragma unroll
;                     for (int n = 0; n < 2; ++n) {
;                         const f32x4 cs0 = rp[2 * n], cs1 = rp[2 * n + 1];
;                         const f32x4 x1 = acc[ai][0][m][n], x2 = acc[ai][1][m][n];
;                         f32x4 o1, o2;
;                         o1[0] = x1[0] * cs0[0] - x2[0] * cs0[1]; o2[0] = x1[0] * cs0[1] + x2[0] * cs0[0];
;                         o1[1] = x1[1] * cs0[2] - x2[1] * cs0[3]; o2[1] = x1[1] * cs0[3] + x2[1] * cs0[2];
;                         o1[2] = x1[2] * cs1[0] - x2[2] * cs1[1]; o2[2] = x1[2] * cs1[1] + x2[2] * cs1[0];
;                         o1[3] = x1[3] * cs1[2] - x2[3] * cs1[3]; o2[3] = x1[3] * cs1[3] + x2[3] * cs1[2];
;                         u32x2 w; w.x = cvt_pk_bf16(o1[0] * sa, o1[1] * sa); w.y = cvt_pk_bf16(o1[2] * sa, o1[3] * sa); *(u32x2*)(d0 + 4 * n) = w;
;                         w.x = cvt_pk_bf16(o2[0] * sa, o2[1] * sa); w.y = cvt_pk_bf16(o2[2] * sa, o2[3] * sa); *(u32x2*)(d0 + 32 + 4 * n) = w;
;                         if (pn == 1) {
;                             w.x = cvt_pk_bf16(o1[0] * sb, o1[1] * sb); w.y = cvt_pk_bf16(o1[2] * sb, o1[3] * sb); *(u32x2*)(d1 + 4 * n) = w;
;                             w.x = cvt_pk_bf16(o2[0] * sb, o2[1] * sb); w.y = cvt_pk_bf16(o2[2] * sb, o2[3] * sb); *(u32x2*)(d1 + 32 + 4 * n) = w;
;                         }
;                     }
.LBB0_877:
	s_andn2_saveexec_b64 s[6:7], s[6:7]
	v_and_b32_e32 v66, 0x7ff, v68
	v_add_u32_e32 v66, 16, v66
	v_and_b32_e32 v69, 63, v68
	v_mov_b32_e32 v73, 64
	s_or_b64 exec, exec, s[6:7]
	v_mov_b32_e32 v67, v33
	v_lshlrev_b64 v[66:67], 8, v[66:67]
	v_lshl_add_u64 v[70:71], v[140:141], 0, v[66:67]
	global_load_dwordx4 v[78:81], v[70:71], off offset:16
	global_load_dwordx4 v[82:85], v[70:71], off
	global_load_dwordx4 v[176:179], v[70:71], off offset:48
	global_load_dwordx4 v[180:183], v[70:71], off offset:32
	v_add_u32_e32 v66, 1, v69
	v_cvt_f32_u32_e32 v66, v66
	v_mul_f32_e32 v67, v161, v66
	v_cmp_gt_f32_e32 vcc, s22, v67
	s_waitcnt vmcnt(2)
	v_mov_b32_e32 v86, v82
	v_cndmask_b32_e32 v67, 0, v232, vcc
	v_fmac_f32_e32 v67, v161, v66
	v_exp_f32_e32 v66, v67
	v_cndmask_b32_e32 v67, 0, v234, vcc
	v_mov_b32_e32 v87, v84
	v_mov_b32_e32 v84, v83
	v_ldexp_f32 v66, v66, v67
	v_div_scale_f32 v67, s[0:1], v66, v66, s80
	v_rcp_f32_e32 v72, v67
	v_mov_b32_e32 v83, v80
	v_mov_b32_e32 v80, v79
	v_mov_b32_e32 v82, v78
	v_fma_f32 v74, -v67, v72, 1.0
	v_fmac_f32_e32 v72, v74, v72
	v_div_scale_f32 v74, vcc, s80, v66, s80
	v_mul_f32_e32 v75, v74, v72
	v_fma_f32 v76, -v67, v75, v74
	v_fmac_f32_e32 v75, v76, v72
	v_fma_f32 v67, -v67, v75, v74
	v_div_fmas_f32 v67, v67, v72, v75
	v_div_fixup_f32 v67, v67, v66, s80
	v_cndmask_b32_e64 v72, v67, v66, s[42:43]
	v_xad_u32 v66, v69, -1, v73
	v_cvt_f32_i32_e32 v66, v66
	v_cmp_lt_i32_e32 vcc, s24, v68
	s_and_b64 s[0:1], s[8:9], vcc
	v_ashrrev_i32_e32 v69, 31, v68
	v_mul_f32_e32 v67, v161, v66
	v_cmp_gt_f32_e32 vcc, s22, v67
	v_pk_mul_f32 v[76:77], v[58:59], v[84:85]
	v_pk_mul_f32 v[58:59], v[58:59], v[86:87]
	v_cndmask_b32_e32 v67, 0, v232, vcc
	v_fmac_f32_e32 v67, v161, v66
	v_exp_f32_e32 v66, v67
	v_lshlrev_b64 v[68:69], 9, v[68:69]
	v_pk_fma_f32 v[76:77], v[62:63], v[86:87], v[76:77] neg_lo:[0,0,1] neg_hi:[0,0,1]
	v_pk_fma_f32 v[58:59], v[62:63], v[84:85], v[58:59]
	v_pk_mul_f32 v[62:63], v[60:61], v[80:81]
	v_lshl_add_u64 v[74:75], s[4:5], 0, v[68:69]
	v_pk_fma_f32 v[62:63], v[64:65], v[82:83], v[62:63] neg_lo:[0,0,1] neg_hi:[0,0,1]
	v_pk_mul_f32 v[60:61], v[60:61], v[82:83]
	v_cndmask_b32_e32 v67, 0, v234, vcc
	v_lshl_add_u64 v[74:75], v[74:75], 0, s[12:13]
	v_pk_fma_f32 v[60:61], v[64:65], v[80:81], v[60:61]
	v_pk_mul_f32 v[64:65], v[76:77], v[72:73] op_sel_hi:[1,0]
	v_pk_mul_f32 v[78:79], v[72:73], v[62:63] op_sel_hi:[0,1]
	v_ldexp_f32 v66, v66, v67
	v_lshl_add_u64 v[74:75], v[74:75], 0, v[32:33]
	v_cvt_pk_bf16_f32 v64, v64, v65
	v_cvt_pk_bf16_f32 v65, v78, v79
	v_mul_f32_e32 v66, 0x3e000000, v66
	global_store_dwordx2 v[74:75], v[64:65], off
	v_pk_mul_f32 v[64:65], v[58:59], v[72:73] op_sel_hi:[1,0]
	v_pk_mul_f32 v[78:79], v[72:73], v[60:61] op_sel_hi:[0,1]
	v_cndmask_b32_e64 v66, v66, 0, s[0:1]
	v_lshl_add_u64 v[68:69], v[142:143], 0, v[68:69]
	v_cvt_pk_bf16_f32 v64, v64, v65
	v_cvt_pk_bf16_f32 v65, v78, v79
	s_and_b64 vcc, exec, s[40:41]
	global_store_dwordx2 v[74:75], v[64:65], off offset:64
	s_cbranch_vccnz .LBB0_881
	v_pk_mul_f32 v[64:65], v[76:77], v[66:67] op_sel_hi:[1,0]
	v_pk_mul_f32 v[62:63], v[62:63], v[66:67] op_sel_hi:[1,0]
	v_pk_mul_f32 v[58:59], v[58:59], v[66:67] op_sel_hi:[1,0]
	v_pk_mul_f32 v[60:61], v[60:61], v[66:67] op_sel_hi:[1,0]
	v_cvt_pk_bf16_f32 v64, v64, v65
	v_cvt_pk_bf16_f32 v65, v62, v63
	v_cvt_pk_bf16_f32 v58, v58, v59
	v_cvt_pk_bf16_f32 v59, v60, v61
	global_store_dwordx2 v[68:69], v[64:65], off
	global_store_dwordx2 v[68:69], v[58:59], off offset:64

; __device__ __forceinline__ unsigned cvt_pk_bf16(float lo, float hi) { const f32x2_cv v = {lo, hi}; const bf16x2_cv b = __builtin_convertvector(v, bf16x2_cv); return __builtin_bit_cast(unsigned, b); }
;     DI void operator()(const f32x4 (&acc)[2][2][4][2], const Unit& u, int wr, int wc, int fr, int fq) const {
;     ...
;                     int pos, jc, L; row_info(g, row, pos, jc, L);
;                     const f32x4* rp = (const f32x4*)(rot + ((size_t)pos * 32 + 8 * fq) * 2);
;                     const float e1 = exp2f((float)(jc + 1) * lg);
;                     const float sa = pn == 0 ? e1 : 0.125f / e1, sb = (g == 0 && row >= 8720) ? 0.f : 0.125f * exp2f((float)(L - 1 - jc) * lg);
;                     bf16_t* d0 = gb + (size_t)(pn == 0 ? CP_QINR : CP_KINR) * G0ROWS + (size_t)row * 256 + wc * 64 + 8 * fq;
;                     bf16_t* d1 = gb + (size_t)CP_KSTR * G0ROWS + (size_t)row * 256 + wc * 64 + 8 * fq;
; #pragma unroll
;                     for (int n = 0; n < 2; ++n) {
;                         const f32x4 cs0 = rp[2 * n], cs1 = rp[2 * n + 1];
;                         const f32x4 x1 = acc[ai][0][m][n], x2 = acc[ai][1][m][n];
;                         f32x4 o1, o2;
;                         o1[0] = x1[0] * cs0[0] - x2[0] * cs0[1]; o2[0] = x1[0] * cs0[1] + x2[0] * cs0[0];
;                         o1[1] = x1[1] * cs0[2] - x2[1] * cs0[3]; o2[1] = x1[1] * cs0[3] + x2[1] * cs0[2];
;                         o1[2] = x1[2] * cs1[0] - x2[2] * cs1[1]; o2[2] = x1[2] * cs1[1] + x2[2] * cs1[0];
;                         o1[3] = x1[3] * cs1[2] - x2[3] * cs1[3]; o2[3] = x1[3] * cs1[3] + x2[3] * cs1[2];
;                         u32x2 w; w.x = cvt_pk_bf16(o1[0] * sa, o1[1] * sa); w.y = cvt_pk_bf16(o1[2] * sa, o1[3] * sa); *(u32x2*)(d0 + 4 * n) = w;
;                         w.x = cvt_pk_bf16(o2[0] * sa, o2[1] * sa); w.y = cvt_pk_bf16(o2[2] * sa, o2[3] * sa); *(u32x2*)(d0 + 32 + 4 * n) = w;
;                         if (pn == 1) {
;                             w.x = cvt_pk_bf16(o1[0] * sb, o1[1] * sb); w.y = cvt_pk_bf16(o1[2] * sb, o1[3] * sb); *(u32x2*)(d1 + 4 * n) = w;
;                             w.x = cvt_pk_bf16(o2[0] * sb, o2[1] * sb); w.y = cvt_pk_bf16(o2[2] * sb, o2[3] * sb); *(u32x2*)(d1 + 32 + 4 * n) = w;
;                         }
;                     }
.LBB0_889:
	s_andn2_saveexec_b64 s[6:7], s[6:7]
	v_and_b32_e32 v50, 0x7ff, v52
	v_add_u32_e32 v50, 16, v50
	v_and_b32_e32 v53, 63, v52
	v_mov_b32_e32 v57, 64
	s_or_b64 exec, exec, s[6:7]
	v_mov_b32_e32 v51, v33
	v_lshlrev_b64 v[50:51], 8, v[50:51]
	v_lshl_add_u64 v[54:55], v[140:141], 0, v[50:51]
	global_load_dwordx4 v[62:65], v[54:55], off offset:16
	global_load_dwordx4 v[66:69], v[54:55], off
	global_load_dwordx4 v[176:179], v[54:55], off offset:48
	global_load_dwordx4 v[180:183], v[54:55], off offset:32
	v_add_u32_e32 v50, 1, v53
	v_cvt_f32_u32_e32 v50, v50
	v_mul_f32_e32 v51, v161, v50
	v_cmp_gt_f32_e32 vcc, s22, v51
	s_waitcnt vmcnt(2)
	v_mov_b32_e32 v70, v66
	v_cndmask_b32_e32 v51, 0, v232, vcc
	v_fmac_f32_e32 v51, v161, v50
	v_exp_f32_e32 v50, v51
	v_cndmask_b32_e32 v51, 0, v234, vcc
	v_mov_b32_e32 v71, v68
	v_mov_b32_e32 v68, v67
	v_ldexp_f32 v50, v50, v51
	v_div_scale_f32 v51, s[0:1], v50, v50, s80
	v_rcp_f32_e32 v56, v51
	v_mov_b32_e32 v67, v64
	v_mov_b32_e32 v64, v63
	v_mov_b32_e32 v66, v62
	v_fma_f32 v58, -v51, v56, 1.0
	v_fmac_f32_e32 v56, v58, v56
	v_div_scale_f32 v58, vcc, s80, v50, s80
	v_mul_f32_e32 v59, v58, v56
	v_fma_f32 v60, -v51, v59, v58
	v_fmac_f32_e32 v59, v60, v56
	v_fma_f32 v51, -v51, v59, v58
	v_div_fmas_f32 v51, v51, v56, v59
	v_div_fixup_f32 v51, v51, v50, s80
	v_cndmask_b32_e64 v56, v51, v50, s[42:43]
	v_xad_u32 v50, v53, -1, v57
	v_cvt_f32_i32_e32 v50, v50
	v_cmp_lt_i32_e32 vcc, s24, v52
	s_and_b64 s[0:1], s[8:9], vcc
	v_ashrrev_i32_e32 v53, 31, v52
	v_mul_f32_e32 v51, v161, v50
	v_cmp_gt_f32_e32 vcc, s22, v51
	v_pk_mul_f32 v[60:61], v[42:43], v[68:69]
	v_pk_mul_f32 v[42:43], v[42:43], v[70:71]
	v_cndmask_b32_e32 v51, 0, v232, vcc
	v_fmac_f32_e32 v51, v161, v50
	v_exp_f32_e32 v50, v51
	v_lshlrev_b64 v[52:53], 9, v[52:53]
	v_pk_fma_f32 v[60:61], v[46:47], v[70:71], v[60:61] neg_lo:[0,0,1] neg_hi:[0,0,1]
	v_pk_fma_f32 v[42:43], v[46:47], v[68:69], v[42:43]
	v_pk_mul_f32 v[46:47], v[44:45], v[64:65]
	v_lshl_add_u64 v[58:59], s[4:5], 0, v[52:53]
	v_pk_fma_f32 v[46:47], v[48:49], v[66:67], v[46:47] neg_lo:[0,0,1] neg_hi:[0,0,1]
	v_pk_mul_f32 v[44:45], v[44:45], v[66:67]
	v_cndmask_b32_e32 v51, 0, v234, vcc
	v_lshl_add_u64 v[58:59], v[58:59], 0, s[12:13]
	v_pk_fma_f32 v[44:45], v[48:49], v[64:65], v[44:45]
	v_pk_mul_f32 v[48:49], v[60:61], v[56:57] op_sel_hi:[1,0]
	v_pk_mul_f32 v[62:63], v[56:57], v[46:47] op_sel_hi:[0,1]
	v_ldexp_f32 v50, v50, v51
	v_lshl_add_u64 v[58:59], v[58:59], 0, v[32:33]
	v_cvt_pk_bf16_f32 v48, v48, v49
	v_cvt_pk_bf16_f32 v49, v62, v63
	v_mul_f32_e32 v50, 0x3e000000, v50
	global_store_dwordx2 v[58:59], v[48:49], off
	v_pk_mul_f32 v[48:49], v[42:43], v[56:57] op_sel_hi:[1,0]
	v_pk_mul_f32 v[62:63], v[56:57], v[44:45] op_sel_hi:[0,1]
	v_cndmask_b32_e64 v50, v50, 0, s[0:1]
	v_lshl_add_u64 v[52:53], v[142:143], 0, v[52:53]
	v_cvt_pk_bf16_f32 v48, v48, v49
	v_cvt_pk_bf16_f32 v49, v62, v63
	s_and_b64 vcc, exec, s[40:41]
	global_store_dwordx2 v[58:59], v[48:49], off offset:64
	s_cbranch_vccnz .LBB0_893
	v_pk_mul_f32 v[48:49], v[60:61], v[50:51] op_sel_hi:[1,0]
	v_pk_mul_f32 v[46:47], v[46:47], v[50:51] op_sel_hi:[1,0]
	v_pk_mul_f32 v[42:43], v[42:43], v[50:51] op_sel_hi:[1,0]
	v_pk_mul_f32 v[44:45], v[44:45], v[50:51] op_sel_hi:[1,0]
	v_cvt_pk_bf16_f32 v48, v48, v49
	v_cvt_pk_bf16_f32 v49, v46, v47
	v_cvt_pk_bf16_f32 v42, v42, v43
	v_cvt_pk_bf16_f32 v43, v44, v45
	global_store_dwordx2 v[52:53], v[48:49], off
	global_store_dwordx2 v[52:53], v[42:43], off offset:64

; __device__ __forceinline__ unsigned cvt_pk_bf16(float lo, float hi) { const f32x2_cv v = {lo, hi}; const bf16x2_cv b = __builtin_convertvector(v, bf16x2_cv); return __builtin_bit_cast(unsigned, b); }
;     DI void operator()(const f32x4 (&acc)[2][2][4][2], const Unit& u, int wr, int wc, int fr, int fq) const {
;     ...
;                     int pos, jc, L; row_info(g, row, pos, jc, L);
;                     const f32x4* rp = (const f32x4*)(rot + ((size_t)pos * 32 + 8 * fq) * 2);
;                     const float e1 = exp2f((float)(jc + 1) * lg);
;                     const float sa = pn == 0 ? e1 : 0.125f / e1, sb = (g == 0 && row >= 8720) ? 0.f : 0.125f * exp2f((float)(L - 1 - jc) * lg);
;                     bf16_t* d0 = gb + (size_t)(pn == 0 ? CP_QINR : CP_KINR) * G0ROWS + (size_t)row * 256 + wc * 64 + 8 * fq;
;                     bf16_t* d1 = gb + (size_t)CP_KSTR * G0ROWS + (size_t)row * 256 + wc * 64 + 8 * fq;
; #pragma unroll
;                     for (int n = 0; n < 2; ++n) {
;                         const f32x4 cs0 = rp[2 * n], cs1 = rp[2 * n + 1];
;                         const f32x4 x1 = acc[ai][0][m][n], x2 = acc[ai][1][m][n];
;                         f32x4 o1, o2;
;                         o1[0] = x1[0] * cs0[0] - x2[0] * cs0[1]; o2[0] = x1[0] * cs0[1] + x2[0] * cs0[0];
;                         o1[1] = x1[1] * cs0[2] - x2[1] * cs0[3]; o2[1] = x1[1] * cs0[3] + x2[1] * cs0[2];
;                         o1[2] = x1[2] * cs1[0] - x2[2] * cs1[1]; o2[2] = x1[2] * cs1[1] + x2[2] * cs1[0];
;                         o1[3] = x1[3] * cs1[2] - x2[3] * cs1[3]; o2[3] = x1[3] * cs1[3] + x2[3] * cs1[2];
;                         u32x2 w; w.x = cvt_pk_bf16(o1[0] * sa, o1[1] * sa); w.y = cvt_pk_bf16(o1[2] * sa, o1[3] * sa); *(u32x2*)(d0 + 4 * n) = w;
;                         w.x = cvt_pk_bf16(o2[0] * sa, o2[1] * sa); w.y = cvt_pk_bf16(o2[2] * sa, o2[3] * sa); *(u32x2*)(d0 + 32 + 4 * n) = w;
;                         if (pn == 1) {
;                             w.x = cvt_pk_bf16(o1[0] * sb, o1[1] * sb); w.y = cvt_pk_bf16(o1[2] * sb, o1[3] * sb); *(u32x2*)(d1 + 4 * n) = w;
;                             w.x = cvt_pk_bf16(o2[0] * sb, o2[1] * sb); w.y = cvt_pk_bf16(o2[2] * sb, o2[3] * sb); *(u32x2*)(d1 + 32 + 4 * n) = w;
;                         }
;                     }
.LBB0_901:
	s_andn2_saveexec_b64 s[6:7], s[6:7]
	v_and_b32_e32 v34, 0x7ff, v36
	v_add_u32_e32 v34, 16, v34
	v_and_b32_e32 v37, 63, v36
	v_mov_b32_e32 v41, 64
	s_or_b64 exec, exec, s[6:7]
	v_mov_b32_e32 v35, v33
	v_lshlrev_b64 v[34:35], 8, v[34:35]
	v_lshl_add_u64 v[38:39], v[140:141], 0, v[34:35]
	global_load_dwordx4 v[46:49], v[38:39], off offset:16
	global_load_dwordx4 v[50:53], v[38:39], off
	global_load_dwordx4 v[176:179], v[38:39], off offset:48
	global_load_dwordx4 v[180:183], v[38:39], off offset:32
	v_add_u32_e32 v34, 1, v37
	v_cvt_f32_u32_e32 v34, v34
	v_mul_f32_e32 v35, v161, v34
	v_cmp_gt_f32_e32 vcc, s22, v35
	s_waitcnt vmcnt(2)
	v_mov_b32_e32 v54, v50
	v_cndmask_b32_e32 v35, 0, v232, vcc
	v_fmac_f32_e32 v35, v161, v34
	v_exp_f32_e32 v34, v35
	v_cndmask_b32_e32 v35, 0, v234, vcc
	v_mov_b32_e32 v55, v52
	v_mov_b32_e32 v52, v51
	v_ldexp_f32 v34, v34, v35
	v_div_scale_f32 v35, s[0:1], v34, v34, s80
	v_rcp_f32_e32 v40, v35
	v_mov_b32_e32 v51, v48
	v_mov_b32_e32 v48, v47
	v_mov_b32_e32 v50, v46
	v_fma_f32 v42, -v35, v40, 1.0
	v_fmac_f32_e32 v40, v42, v40
	v_div_scale_f32 v42, vcc, s80, v34, s80
	v_mul_f32_e32 v43, v42, v40
	v_fma_f32 v44, -v35, v43, v42
	v_fmac_f32_e32 v43, v44, v40
	v_fma_f32 v35, -v35, v43, v42
	v_div_fmas_f32 v35, v35, v40, v43
	v_div_fixup_f32 v35, v35, v34, s80
	v_cndmask_b32_e64 v40, v35, v34, s[42:43]
	v_xad_u32 v34, v37, -1, v41
	v_cvt_f32_i32_e32 v34, v34
	v_cmp_lt_i32_e32 vcc, s24, v36
	s_and_b64 s[0:1], s[8:9], vcc
	v_ashrrev_i32_e32 v37, 31, v36
	v_mul_f32_e32 v35, v161, v34
	v_cmp_gt_f32_e32 vcc, s22, v35
	v_pk_mul_f32 v[44:45], v[24:25], v[52:53]
	v_pk_mul_f32 v[24:25], v[24:25], v[54:55]
	v_cndmask_b32_e32 v35, 0, v232, vcc
	v_fmac_f32_e32 v35, v161, v34
	v_exp_f32_e32 v34, v35
	v_lshlrev_b64 v[36:37], 9, v[36:37]
	v_pk_fma_f32 v[44:45], v[28:29], v[54:55], v[44:45] neg_lo:[0,0,1] neg_hi:[0,0,1]
	v_pk_fma_f32 v[24:25], v[28:29], v[52:53], v[24:25]
	v_pk_mul_f32 v[28:29], v[26:27], v[48:49]
	v_lshl_add_u64 v[42:43], s[4:5], 0, v[36:37]
	v_pk_fma_f32 v[28:29], v[30:31], v[50:51], v[28:29] neg_lo:[0,0,1] neg_hi:[0,0,1]
	v_pk_mul_f32 v[26:27], v[26:27], v[50:51]
	v_cndmask_b32_e32 v35, 0, v234, vcc
	v_lshl_add_u64 v[42:43], v[42:43], 0, s[12:13]
	v_pk_fma_f32 v[26:27], v[30:31], v[48:49], v[26:27]
	v_pk_mul_f32 v[30:31], v[44:45], v[40:41] op_sel_hi:[1,0]
	v_pk_mul_f32 v[46:47], v[40:41], v[28:29] op_sel_hi:[0,1]
	v_ldexp_f32 v34, v34, v35
	v_lshl_add_u64 v[42:43], v[42:43], 0, v[32:33]
	v_cvt_pk_bf16_f32 v30, v30, v31
	v_cvt_pk_bf16_f32 v31, v46, v47
	v_mul_f32_e32 v34, 0x3e000000, v34
	global_store_dwordx2 v[42:43], v[30:31], off
	v_pk_mul_f32 v[30:31], v[24:25], v[40:41] op_sel_hi:[1,0]
	v_pk_mul_f32 v[46:47], v[40:41], v[26:27] op_sel_hi:[0,1]
	v_cndmask_b32_e64 v34, v34, 0, s[0:1]
	v_lshl_add_u64 v[36:37], v[142:143], 0, v[36:37]
	v_cvt_pk_bf16_f32 v30, v30, v31
	v_cvt_pk_bf16_f32 v31, v46, v47
	s_and_b64 vcc, exec, s[40:41]
	global_store_dwordx2 v[42:43], v[30:31], off offset:64
	s_cbranch_vccnz .LBB0_905
	v_pk_mul_f32 v[30:31], v[44:45], v[34:35] op_sel_hi:[1,0]
	v_pk_mul_f32 v[28:29], v[28:29], v[34:35] op_sel_hi:[1,0]
	v_pk_mul_f32 v[24:25], v[24:25], v[34:35] op_sel_hi:[1,0]
	v_pk_mul_f32 v[26:27], v[26:27], v[34:35] op_sel_hi:[1,0]
	v_cvt_pk_bf16_f32 v30, v30, v31
	v_cvt_pk_bf16_f32 v31, v28, v29
	v_cvt_pk_bf16_f32 v24, v24, v25
	v_cvt_pk_bf16_f32 v25, v26, v27
	global_store_dwordx2 v[36:37], v[30:31], off
	global_store_dwordx2 v[36:37], v[24:25], off offset:64

; __device__ __forceinline__ unsigned cvt_pk_bf16(float lo, float hi) { const f32x2_cv v = {lo, hi}; const bf16x2_cv b = __builtin_convertvector(v, bf16x2_cv); return __builtin_bit_cast(unsigned, b); }
;     DI void operator()(const f32x4 (&acc)[2][2][4][2], const Unit& u, int wr, int wc, int fr, int fq) const {
;     ...
;                     int pos, jc, L; row_info(g, row, pos, jc, L);
;                     const f32x4* rp = (const f32x4*)(rot + ((size_t)pos * 32 + 8 * fq) * 2);
;                     const float e1 = exp2f((float)(jc + 1) * lg);
;                     const float sa = pn == 0 ? e1 : 0.125f / e1, sb = (g == 0 && row >= 8720) ? 0.f : 0.125f * exp2f((float)(L - 1 - jc) * lg);
;                     bf16_t* d0 = gb + (size_t)(pn == 0 ? CP_QINR : CP_KINR) * G0ROWS + (size_t)row * 256 + wc * 64 + 8 * fq;
;                     bf16_t* d1 = gb + (size_t)CP_KSTR * G0ROWS + (size_t)row * 256 + wc * 64 + 8 * fq;
; #pragma unroll
;                     for (int n = 0; n < 2; ++n) {
;                         const f32x4 cs0 = rp[2 * n], cs1 = rp[2 * n + 1];
;                         const f32x4 x1 = acc[ai][0][m][n], x2 = acc[ai][1][m][n];
;                         f32x4 o1, o2;
;                         o1[0] = x1[0] * cs0[0] - x2[0] * cs0[1]; o2[0] = x1[0] * cs0[1] + x2[0] * cs0[0];
;                         o1[1] = x1[1] * cs0[2] - x2[1] * cs0[3]; o2[1] = x1[1] * cs0[3] + x2[1] * cs0[2];
;                         o1[2] = x1[2] * cs1[0] - x2[2] * cs1[1]; o2[2] = x1[2] * cs1[1] + x2[2] * cs1[0];
;                         o1[3] = x1[3] * cs1[2] - x2[3] * cs1[3]; o2[3] = x1[3] * cs1[3] + x2[3] * cs1[2];
;                         u32x2 w; w.x = cvt_pk_bf16(o1[0] * sa, o1[1] * sa); w.y = cvt_pk_bf16(o1[2] * sa, o1[3] * sa); *(u32x2*)(d0 + 4 * n) = w;
;                         w.x = cvt_pk_bf16(o2[0] * sa, o2[1] * sa); w.y = cvt_pk_bf16(o2[2] * sa, o2[3] * sa); *(u32x2*)(d0 + 32 + 4 * n) = w;
;                         if (pn == 1) {
;                             w.x = cvt_pk_bf16(o1[0] * sb, o1[1] * sb); w.y = cvt_pk_bf16(o1[2] * sb, o1[3] * sb); *(u32x2*)(d1 + 4 * n) = w;
;                             w.x = cvt_pk_bf16(o2[0] * sb, o2[1] * sb); w.y = cvt_pk_bf16(o2[2] * sb, o2[3] * sb); *(u32x2*)(d1 + 32 + 4 * n) = w;
;                         }
;                     }
.LBB0_913:
	s_andn2_saveexec_b64 s[6:7], s[6:7]
	v_and_b32_e32 v16, 0x7ff, v18
	v_add_u32_e32 v16, 16, v16
	v_and_b32_e32 v19, 63, v18
	v_mov_b32_e32 v23, 64
	s_or_b64 exec, exec, s[6:7]
	v_mov_b32_e32 v17, v33
	v_lshlrev_b64 v[16:17], 8, v[16:17]
	v_lshl_add_u64 v[20:21], v[140:141], 0, v[16:17]
	global_load_dwordx4 v[28:31], v[20:21], off offset:16
	global_load_dwordx4 v[34:37], v[20:21], off
	global_load_dwordx4 v[176:179], v[20:21], off offset:48
	global_load_dwordx4 v[180:183], v[20:21], off offset:32
	v_add_u32_e32 v16, 1, v19
	v_cvt_f32_u32_e32 v16, v16
	v_mul_f32_e32 v17, v161, v16
	v_cmp_gt_f32_e32 vcc, s22, v17
	s_waitcnt vmcnt(2)
	v_mov_b32_e32 v38, v34
	v_cndmask_b32_e32 v17, 0, v232, vcc
	v_fmac_f32_e32 v17, v161, v16
	v_exp_f32_e32 v16, v17
	v_cndmask_b32_e32 v17, 0, v234, vcc
	v_mov_b32_e32 v39, v36
	v_mov_b32_e32 v36, v35
	v_ldexp_f32 v16, v16, v17
	v_div_scale_f32 v17, s[0:1], v16, v16, s80
	v_rcp_f32_e32 v22, v17
	v_mov_b32_e32 v35, v30
	v_mov_b32_e32 v30, v29
	v_mov_b32_e32 v34, v28
	v_fma_f32 v24, -v17, v22, 1.0
	v_fmac_f32_e32 v22, v24, v22
	v_div_scale_f32 v24, vcc, s80, v16, s80
	v_mul_f32_e32 v25, v24, v22
	v_fma_f32 v26, -v17, v25, v24
	v_fmac_f32_e32 v25, v26, v22
	v_fma_f32 v17, -v17, v25, v24
	v_div_fmas_f32 v17, v17, v22, v25
	v_div_fixup_f32 v17, v17, v16, s80
	v_cndmask_b32_e64 v22, v17, v16, s[42:43]
	v_xad_u32 v16, v19, -1, v23
	v_cvt_f32_i32_e32 v16, v16
	v_cmp_lt_i32_e32 vcc, s24, v18
	s_and_b64 s[0:1], s[8:9], vcc
	v_ashrrev_i32_e32 v19, 31, v18
	v_mul_f32_e32 v17, v161, v16
	v_cmp_gt_f32_e32 vcc, s22, v17
	v_pk_mul_f32 v[26:27], v[8:9], v[36:37]
	v_pk_mul_f32 v[8:9], v[8:9], v[38:39]
	v_cndmask_b32_e32 v17, 0, v232, vcc
	v_fmac_f32_e32 v17, v161, v16
	v_exp_f32_e32 v16, v17
	v_lshlrev_b64 v[18:19], 9, v[18:19]
	v_pk_fma_f32 v[26:27], v[12:13], v[38:39], v[26:27] neg_lo:[0,0,1] neg_hi:[0,0,1]
	v_pk_fma_f32 v[8:9], v[12:13], v[36:37], v[8:9]
	v_pk_mul_f32 v[12:13], v[10:11], v[30:31]
	v_lshl_add_u64 v[24:25], s[4:5], 0, v[18:19]
	v_pk_fma_f32 v[12:13], v[14:15], v[34:35], v[12:13] neg_lo:[0,0,1] neg_hi:[0,0,1]
	v_pk_mul_f32 v[10:11], v[10:11], v[34:35]
	v_cndmask_b32_e32 v17, 0, v234, vcc
	v_lshl_add_u64 v[24:25], v[24:25], 0, s[12:13]
	v_pk_fma_f32 v[10:11], v[14:15], v[30:31], v[10:11]
	v_pk_mul_f32 v[14:15], v[26:27], v[22:23] op_sel_hi:[1,0]
	v_pk_mul_f32 v[28:29], v[22:23], v[12:13] op_sel_hi:[0,1]
	v_ldexp_f32 v16, v16, v17
	v_lshl_add_u64 v[24:25], v[24:25], 0, v[32:33]
	v_cvt_pk_bf16_f32 v14, v14, v15
	v_cvt_pk_bf16_f32 v15, v28, v29
	v_mul_f32_e32 v16, 0x3e000000, v16
	global_store_dwordx2 v[24:25], v[14:15], off
	v_pk_mul_f32 v[14:15], v[8:9], v[22:23] op_sel_hi:[1,0]
	v_pk_mul_f32 v[28:29], v[22:23], v[10:11] op_sel_hi:[0,1]
	v_cndmask_b32_e64 v16, v16, 0, s[0:1]
	v_lshl_add_u64 v[18:19], v[142:143], 0, v[18:19]
	v_cvt_pk_bf16_f32 v14, v14, v15
	v_cvt_pk_bf16_f32 v15, v28, v29
	s_and_b64 vcc, exec, s[40:41]
	global_store_dwordx2 v[24:25], v[14:15], off offset:64
	s_cbranch_vccnz .LBB0_917
	v_pk_mul_f32 v[14:15], v[26:27], v[16:17] op_sel_hi:[1,0]
	v_pk_mul_f32 v[12:13], v[12:13], v[16:17] op_sel_hi:[1,0]
	v_pk_mul_f32 v[8:9], v[8:9], v[16:17] op_sel_hi:[1,0]
	v_pk_mul_f32 v[10:11], v[10:11], v[16:17] op_sel_hi:[1,0]
	v_cvt_pk_bf16_f32 v14, v14, v15
	v_cvt_pk_bf16_f32 v15, v12, v13
	v_cvt_pk_bf16_f32 v8, v8, v9
	v_cvt_pk_bf16_f32 v9, v10, v11
	global_store_dwordx2 v[18:19], v[14:15], off
	global_store_dwordx2 v[18:19], v[8:9], off offset:64
